# hand-written exact top-256 selection replaces compiler unrolled selection (same algorithm: 1024-bin histogram + exact tie ranking), fewer barriers, n-limited passes
# speedup vs baseline: 1.0904x; 1.0904x over previous
; DI unsigned cvtpk(float lo, float hi) { f32x2_t v = {lo, hi}; bf16x2_t b = __builtin_convertvector(v, bf16x2_t); return __builtin_bit_cast(unsigned, b); }
; DI void lds_barrier() { asm volatile("s_waitcnt lgkmcnt(0)" ::: "memory"); __builtin_amdgcn_s_barrier(); asm volatile("" ::: "memory"); }
; DI float ord2f(unsigned k) { return __uint_as_float((k & 0x80000000u) ? (k ^ 0x80000000u) : ~k); }
; DI void selectA_item(const Params& p, int item, int next_item, char* lds, bf16x8 (&qf)[4], float (&wq)[16]) {
;     ...
;   { u32x2 w; w.x = cvtpk(pcv.x, pcv.y); w.y = cvtpk(pcv.z, pcv.w); ((u32x2*)(p.ws + WS_PBF))[(size_t)item * 512 + tid] = w; }
;   lds_barrier();
;   {
;     const int g = wid >> 1, gt = tid & 127, upper = wid & 1;
;     const int t = t0 + g, n = t + 1;
;     const bool big = n > 256;
;     const float* scq = sc + g * 8192;
;     unsigned short* out = SEL + (rowb + t) * 256;
;     int* histq = hist + g * 1024;
;     unsigned long long* clq = clist + g * 128;
;     int* mq = misc + 32 + g * 8;
;     const float lo = ord2f(mm[g * 2]), hi = ord2f(mm[g * 2 + 1]);
;     const float scale = (hi > lo) ? 1023.f / (hi - lo) : 0.f;
;     for (int i = gt; i < 1024; i += 128) histq[i] = 0;
;     if (gt == 0) { mq[0] = 0; mq[6] = 0; }
;     lds_barrier();
;     float uu[64];
; #pragma unroll
;     for (int i = 0; i < 64; ++i) { const int idx = gt + 128 * i; const float v = (idx < n) ? scq[idx] : lo; const float u = (v - lo) * scale; uu[i] = u;
;       if (big && idx < n) { int bb = (int)u; bb = bb > 1023 ? 1023 : bb; atomicAdd(&histq[bb], 1); } }
.LBB0_417:
	v_readlane_b32 s0, v254, 26
	v_readlane_b32 s1, v254, 27
	s_waitcnt vmcnt(0)
	v_cvt_pk_bf16_f32 v0, v16, v17
	v_cvt_pk_bf16_f32 v1, v18, v19
	v_lshl_add_u64 v[2:3], v[76:77], 3, s[0:1]
	global_store_dwordx2 v[2:3], v[0:1], off
	v_and_b32_e32 v180, 0x7f, v182
	v_lshrrev_b32_e32 v0, 7, v182
	v_lshlrev_b32_e32 v1, 12, v0
	v_lshl_add_u32 v1, v180, 5, v1
	v_add_u32_e32 v1, 0x20000, v1
	v_mov_b32_e32 v2, 0
	v_mov_b32_e32 v3, 0
	v_mov_b32_e32 v4, 0
	v_mov_b32_e32 v5, 0
	ds_write_b128 v1, v[2:5]
	ds_write_b128 v1, v[2:5] offset:16
	v_lshlrev_b32_e32 v6, 10, v0
	v_lshl_add_u32 v6, v180, 3, v6
	v_add_u32_e32 v6, 0x24180, v6
	ds_write_b64 v6, v[2:3]
	v_lshlrev_b32_e32 v7, 5, v0
	v_add_u32_e32 v7, 0x24080, v7
	v_cmp_eq_u32_e32 vcc, 0, v180
	s_and_saveexec_b64 s[0:1], vcc
	ds_write_b128 v7, v[2:5]
	ds_write_b128 v7, v[2:5] offset:16
	s_or_b64 exec, exec, s[0:1]
	s_waitcnt lgkmcnt(0)
	s_barrier
	s_lshl_b64 s[82:83], s[52:53], 13
	v_lshrrev_b32_e32 v0, 6, v182
	v_mov_b32_e32 v204, 0x80000000
	v_readfirstlane_b32 s36, v0
	v_readlane_b32 s39, v254, 58
	v_readlane_b32 s62, v254, 22
	v_readlane_b32 s63, v254, 23
	v_mov_b32_e32 v205, 0x2404c
	v_mov_b32_e32 v206, 1
	s_lshr_b32 s37, s36, 1
	s_and_b32 s38, s36, 1
	s_add_i32 s40, s39, s37
	s_add_i32 s40, s40, 1
	s_lshl_b32 s41, s37, 12
	s_add_i32 s41, s41, 0x20000
	s_lshl_b32 s42, s37, 5
	s_add_i32 s42, s42, 0x24080
	s_lshl_b32 s43, s37, 10
	s_add_i32 s43, s43, 0x24180
	s_lshl_b32 s0, s52, 13
	s_add_i32 s0, s0, s40
	s_add_i32 s0, s0, -1
	s_lshl_b32 s0, s0, 9
	s_add_u32 s62, s62, s0
	s_addc_u32 s63, s63, 0
	s_lshl_b32 s84, s37, 15
	v_lshl_add_u32 v181, v180, 2, s84
	v_mov_b32_e32 v207, s42
	s_mov_b32 s65, 0
	s_cmp_gt_u32 s40, 0x100
	s_cbranch_scc1 .Lsel_big
	v_cmp_gt_u32_e32 vcc, s40, v180
	s_and_saveexec_b64 s[0:1], vcc
	v_lshlrev_b32_e32 v0, 1, v180
	global_store_short v0, v180, s[62:63]
	s_or_b64 exec, exec, s[0:1]
	v_add_u32_e32 v1, 0x80, v180
	v_cmp_gt_u32_e32 vcc, s40, v1
	s_and_saveexec_b64 s[0:1], vcc
	v_lshlrev_b32_e32 v0, 1, v1
	global_store_short v0, v1, s[62:63]
	s_or_b64 exec, exec, s[0:1]
	s_mov_b32 s65, 1
	s_branch .Lsel_B_done
.Lsel_big:
	s_lshl_b32 s2, s37, 3
	s_add_i32 s2, s2, 0x24060
	v_mov_b32_e32 v0, s2
	ds_read_b64 v[2:3], v0
	s_waitcnt lgkmcnt(0)
	v_ashrrev_i32_e32 v4, 31, v2
	v_ashrrev_i32_e32 v5, 31, v3
	v_and_b32_e32 v4, 0x7fffffff, v4
	v_and_b32_e32 v5, 0x7fffffff, v5
	v_not_b32_e32 v4, v4
	v_not_b32_e32 v5, v5
	v_xor_b32_e32 v192, v2, v4
	v_xor_b32_e32 v5, v3, v5
	v_sub_f32_e32 v6, v5, v192
	v_cmp_gt_f32_e32 vcc, v5, v192
	v_rcp_f32_e32 v6, v6
	s_nop 1
	v_mul_f32_e32 v6, 0x447fc000, v6
	v_cndmask_b32_e32 v193, 0, v6, vcc
.Lsel_B_0:
	s_cmp_lt_u32 s40, 0x400
	s_cbranch_scc1 .Lsel_B_0_part
	ds_read_b32 v8, v181 offset:0
	ds_read_b32 v9, v181 offset:512
	ds_read_b32 v10, v181 offset:1024
	ds_read_b32 v11, v181 offset:1536
	ds_read_b32 v12, v181 offset:2048
	ds_read_b32 v13, v181 offset:2560
	ds_read_b32 v14, v181 offset:3072
	ds_read_b32 v15, v181 offset:3584
	s_waitcnt lgkmcnt(7)
	v_sub_f32_e32 v8, v8, v192
	v_mul_f32_e32 v116, v8, v193
	v_cvt_i32_f32_e32 v16, v116
	v_min_i32_e32 v16, 0x3ff, v16
	v_lshl_add_u32 v16, v16, 2, s41
	ds_add_u32 v16, v206
	s_waitcnt lgkmcnt(7)
	v_sub_f32_e32 v9, v9, v192
	v_mul_f32_e32 v117, v9, v193
	v_cvt_i32_f32_e32 v17, v117
	v_min_i32_e32 v17, 0x3ff, v17
	v_lshl_add_u32 v17, v17, 2, s41
	ds_add_u32 v17, v206
	s_waitcnt lgkmcnt(7)
	v_sub_f32_e32 v10, v10, v192
	v_mul_f32_e32 v118, v10, v193
	v_cvt_i32_f32_e32 v18, v118
	v_min_i32_e32 v18, 0x3ff, v18
	v_lshl_add_u32 v18, v18, 2, s41
	ds_add_u32 v18, v206
	s_waitcnt lgkmcnt(7)
	v_sub_f32_e32 v11, v11, v192
	v_mul_f32_e32 v119, v11, v193
	v_cvt_i32_f32_e32 v19, v119
	v_min_i32_e32 v19, 0x3ff, v19
	v_lshl_add_u32 v19, v19, 2, s41
	ds_add_u32 v19, v206
	s_waitcnt lgkmcnt(7)
	v_sub_f32_e32 v12, v12, v192
	v_mul_f32_e32 v120, v12, v193
	v_cvt_i32_f32_e32 v20, v120
	v_min_i32_e32 v20, 0x3ff, v20
	v_lshl_add_u32 v20, v20, 2, s41
	ds_add_u32 v20, v206
	s_waitcnt lgkmcnt(7)
	v_sub_f32_e32 v13, v13, v192
	v_mul_f32_e32 v121, v13, v193
	v_cvt_i32_f32_e32 v21, v121
	v_min_i32_e32 v21, 0x3ff, v21
	v_lshl_add_u32 v21, v21, 2, s41
	ds_add_u32 v21, v206
	s_waitcnt lgkmcnt(7)
	v_sub_f32_e32 v14, v14, v192
	v_mul_f32_e32 v122, v14, v193
	v_cvt_i32_f32_e32 v22, v122
	v_min_i32_e32 v22, 0x3ff, v22
	v_lshl_add_u32 v22, v22, 2, s41
	ds_add_u32 v22, v206
	s_waitcnt lgkmcnt(7)
	v_sub_f32_e32 v15, v15, v192
	v_mul_f32_e32 v123, v15, v193
	v_cvt_i32_f32_e32 v23, v123
	v_min_i32_e32 v23, 0x3ff, v23
	v_lshl_add_u32 v23, v23, 2, s41
	ds_add_u32 v23, v206
.Lsel_B_1:
	s_cmp_le_u32 s40, 0x400
	s_cbranch_scc1 .Lsel_B_done
	s_cmp_lt_u32 s40, 0x800
	s_cbranch_scc1 .Lsel_B_1_part
	ds_read_b32 v8, v181 offset:4096
	ds_read_b32 v9, v181 offset:4608
	ds_read_b32 v10, v181 offset:5120
	ds_read_b32 v11, v181 offset:5632
	ds_read_b32 v12, v181 offset:6144
	ds_read_b32 v13, v181 offset:6656
	ds_read_b32 v14, v181 offset:7168
	ds_read_b32 v15, v181 offset:7680
	s_waitcnt lgkmcnt(7)
	v_sub_f32_e32 v8, v8, v192
	v_mul_f32_e32 v124, v8, v193
	v_cvt_i32_f32_e32 v16, v124
	v_min_i32_e32 v16, 0x3ff, v16
	v_lshl_add_u32 v16, v16, 2, s41
	ds_add_u32 v16, v206
	s_waitcnt lgkmcnt(7)
	v_sub_f32_e32 v9, v9, v192
	v_mul_f32_e32 v125, v9, v193
	v_cvt_i32_f32_e32 v17, v125
	v_min_i32_e32 v17, 0x3ff, v17
	v_lshl_add_u32 v17, v17, 2, s41
	ds_add_u32 v17, v206
	s_waitcnt lgkmcnt(7)
	v_sub_f32_e32 v10, v10, v192
	v_mul_f32_e32 v126, v10, v193
	v_cvt_i32_f32_e32 v18, v126
	v_min_i32_e32 v18, 0x3ff, v18
	v_lshl_add_u32 v18, v18, 2, s41
	ds_add_u32 v18, v206
	s_waitcnt lgkmcnt(7)
	v_sub_f32_e32 v11, v11, v192
	v_mul_f32_e32 v127, v11, v193
	v_cvt_i32_f32_e32 v19, v127
	v_min_i32_e32 v19, 0x3ff, v19
	v_lshl_add_u32 v19, v19, 2, s41
	ds_add_u32 v19, v206
	s_waitcnt lgkmcnt(7)
	v_sub_f32_e32 v12, v12, v192
	v_mul_f32_e32 v128, v12, v193
	v_cvt_i32_f32_e32 v20, v128
	v_min_i32_e32 v20, 0x3ff, v20
	v_lshl_add_u32 v20, v20, 2, s41
	ds_add_u32 v20, v206
	s_waitcnt lgkmcnt(7)
	v_sub_f32_e32 v13, v13, v192
	v_mul_f32_e32 v129, v13, v193
	v_cvt_i32_f32_e32 v21, v129
	v_min_i32_e32 v21, 0x3ff, v21
	v_lshl_add_u32 v21, v21, 2, s41
	ds_add_u32 v21, v206
	s_waitcnt lgkmcnt(7)
	v_sub_f32_e32 v14, v14, v192
	v_mul_f32_e32 v130, v14, v193
	v_cvt_i32_f32_e32 v22, v130
	v_min_i32_e32 v22, 0x3ff, v22
	v_lshl_add_u32 v22, v22, 2, s41
	ds_add_u32 v22, v206
	s_waitcnt lgkmcnt(7)
	v_sub_f32_e32 v15, v15, v192
	v_mul_f32_e32 v131, v15, v193
	v_cvt_i32_f32_e32 v23, v131
	v_min_i32_e32 v23, 0x3ff, v23
	v_lshl_add_u32 v23, v23, 2, s41
	ds_add_u32 v23, v206
; DI void selectA_item(const Params& p, int item, int next_item, char* lds, bf16x8 (&qf)[4], float (&wq)[16]) {
;     ...
;     for (int i = 0; i < 64; ++i) { const int idx = gt + 128 * i; const float v = (idx < n) ? scq[idx] : lo; const float u = (v - lo) * scale; uu[i] = u;
;       if (big && idx < n) { int bb = (int)u; bb = bb > 1023 ? 1023 : bb; atomicAdd(&histq[bb], 1); } }
.Lsel_B_2:
	s_cmp_le_u32 s40, 0x800
	s_cbranch_scc1 .Lsel_B_done
	s_cmp_lt_u32 s40, 0xc00
	s_cbranch_scc1 .Lsel_B_2_part
	ds_read_b32 v8, v181 offset:8192
	ds_read_b32 v9, v181 offset:8704
	ds_read_b32 v10, v181 offset:9216
	ds_read_b32 v11, v181 offset:9728
	ds_read_b32 v12, v181 offset:10240
	ds_read_b32 v13, v181 offset:10752
	ds_read_b32 v14, v181 offset:11264
	ds_read_b32 v15, v181 offset:11776
	s_waitcnt lgkmcnt(7)
	v_sub_f32_e32 v8, v8, v192
	v_mul_f32_e32 v132, v8, v193
	v_cvt_i32_f32_e32 v16, v132
	v_min_i32_e32 v16, 0x3ff, v16
	v_lshl_add_u32 v16, v16, 2, s41
	ds_add_u32 v16, v206
	s_waitcnt lgkmcnt(7)
	v_sub_f32_e32 v9, v9, v192
	v_mul_f32_e32 v133, v9, v193
	v_cvt_i32_f32_e32 v17, v133
	v_min_i32_e32 v17, 0x3ff, v17
	v_lshl_add_u32 v17, v17, 2, s41
	ds_add_u32 v17, v206
	s_waitcnt lgkmcnt(7)
	v_sub_f32_e32 v10, v10, v192
	v_mul_f32_e32 v134, v10, v193
	v_cvt_i32_f32_e32 v18, v134
	v_min_i32_e32 v18, 0x3ff, v18
	v_lshl_add_u32 v18, v18, 2, s41
	ds_add_u32 v18, v206
	s_waitcnt lgkmcnt(7)
	v_sub_f32_e32 v11, v11, v192
	v_mul_f32_e32 v135, v11, v193
	v_cvt_i32_f32_e32 v19, v135
	v_min_i32_e32 v19, 0x3ff, v19
	v_lshl_add_u32 v19, v19, 2, s41
	ds_add_u32 v19, v206
	s_waitcnt lgkmcnt(7)
	v_sub_f32_e32 v12, v12, v192
	v_mul_f32_e32 v136, v12, v193
	v_cvt_i32_f32_e32 v20, v136
	v_min_i32_e32 v20, 0x3ff, v20
	v_lshl_add_u32 v20, v20, 2, s41
	ds_add_u32 v20, v206
	s_waitcnt lgkmcnt(7)
	v_sub_f32_e32 v13, v13, v192
	v_mul_f32_e32 v137, v13, v193
	v_cvt_i32_f32_e32 v21, v137
	v_min_i32_e32 v21, 0x3ff, v21
	v_lshl_add_u32 v21, v21, 2, s41
	ds_add_u32 v21, v206
	s_waitcnt lgkmcnt(7)
	v_sub_f32_e32 v14, v14, v192
	v_mul_f32_e32 v138, v14, v193
	v_cvt_i32_f32_e32 v22, v138
	v_min_i32_e32 v22, 0x3ff, v22
	v_lshl_add_u32 v22, v22, 2, s41
	ds_add_u32 v22, v206
	s_waitcnt lgkmcnt(7)
	v_sub_f32_e32 v15, v15, v192
	v_mul_f32_e32 v139, v15, v193
	v_cvt_i32_f32_e32 v23, v139
	v_min_i32_e32 v23, 0x3ff, v23
	v_lshl_add_u32 v23, v23, 2, s41
	ds_add_u32 v23, v206
.Lsel_B_3:
	s_cmp_le_u32 s40, 0xc00
	s_cbranch_scc1 .Lsel_B_done
	s_cmp_lt_u32 s40, 0x1000
	s_cbranch_scc1 .Lsel_B_3_part
	ds_read_b32 v8, v181 offset:12288
	ds_read_b32 v9, v181 offset:12800
	ds_read_b32 v10, v181 offset:13312
	ds_read_b32 v11, v181 offset:13824
	ds_read_b32 v12, v181 offset:14336
	ds_read_b32 v13, v181 offset:14848
	ds_read_b32 v14, v181 offset:15360
	ds_read_b32 v15, v181 offset:15872
	s_waitcnt lgkmcnt(7)
	v_sub_f32_e32 v8, v8, v192
	v_mul_f32_e32 v140, v8, v193
	v_cvt_i32_f32_e32 v16, v140
	v_min_i32_e32 v16, 0x3ff, v16
	v_lshl_add_u32 v16, v16, 2, s41
	ds_add_u32 v16, v206
	s_waitcnt lgkmcnt(7)
	v_sub_f32_e32 v9, v9, v192
	v_mul_f32_e32 v141, v9, v193
	v_cvt_i32_f32_e32 v17, v141
	v_min_i32_e32 v17, 0x3ff, v17
	v_lshl_add_u32 v17, v17, 2, s41
	ds_add_u32 v17, v206
	s_waitcnt lgkmcnt(7)
	v_sub_f32_e32 v10, v10, v192
	v_mul_f32_e32 v142, v10, v193
	v_cvt_i32_f32_e32 v18, v142
	v_min_i32_e32 v18, 0x3ff, v18
	v_lshl_add_u32 v18, v18, 2, s41
	ds_add_u32 v18, v206
	s_waitcnt lgkmcnt(7)
	v_sub_f32_e32 v11, v11, v192
	v_mul_f32_e32 v143, v11, v193
	v_cvt_i32_f32_e32 v19, v143
	v_min_i32_e32 v19, 0x3ff, v19
	v_lshl_add_u32 v19, v19, 2, s41
	ds_add_u32 v19, v206
	s_waitcnt lgkmcnt(7)
	v_sub_f32_e32 v12, v12, v192
	v_mul_f32_e32 v144, v12, v193
	v_cvt_i32_f32_e32 v20, v144
	v_min_i32_e32 v20, 0x3ff, v20
	v_lshl_add_u32 v20, v20, 2, s41
	ds_add_u32 v20, v206
	s_waitcnt lgkmcnt(7)
	v_sub_f32_e32 v13, v13, v192
	v_mul_f32_e32 v145, v13, v193
	v_cvt_i32_f32_e32 v21, v145
	v_min_i32_e32 v21, 0x3ff, v21
	v_lshl_add_u32 v21, v21, 2, s41
	ds_add_u32 v21, v206
	s_waitcnt lgkmcnt(7)
	v_sub_f32_e32 v14, v14, v192
	v_mul_f32_e32 v146, v14, v193
	v_cvt_i32_f32_e32 v22, v146
	v_min_i32_e32 v22, 0x3ff, v22
	v_lshl_add_u32 v22, v22, 2, s41
	ds_add_u32 v22, v206
	s_waitcnt lgkmcnt(7)
	v_sub_f32_e32 v15, v15, v192
	v_mul_f32_e32 v147, v15, v193
	v_cvt_i32_f32_e32 v23, v147
	v_min_i32_e32 v23, 0x3ff, v23
	v_lshl_add_u32 v23, v23, 2, s41
	ds_add_u32 v23, v206
.Lsel_B_4:
	s_cmp_le_u32 s40, 0x1000
	s_cbranch_scc1 .Lsel_B_done
	s_cmp_lt_u32 s40, 0x1400
	s_cbranch_scc1 .Lsel_B_4_part
	ds_read_b32 v8, v181 offset:16384
	ds_read_b32 v9, v181 offset:16896
	ds_read_b32 v10, v181 offset:17408
	ds_read_b32 v11, v181 offset:17920
	ds_read_b32 v12, v181 offset:18432
	ds_read_b32 v13, v181 offset:18944
	ds_read_b32 v14, v181 offset:19456
	ds_read_b32 v15, v181 offset:19968
	s_waitcnt lgkmcnt(7)
	v_sub_f32_e32 v8, v8, v192
	v_mul_f32_e32 v148, v8, v193
	v_cvt_i32_f32_e32 v16, v148
	v_min_i32_e32 v16, 0x3ff, v16
	v_lshl_add_u32 v16, v16, 2, s41
	ds_add_u32 v16, v206
	s_waitcnt lgkmcnt(7)
	v_sub_f32_e32 v9, v9, v192
	v_mul_f32_e32 v149, v9, v193
	v_cvt_i32_f32_e32 v17, v149
	v_min_i32_e32 v17, 0x3ff, v17
	v_lshl_add_u32 v17, v17, 2, s41
	ds_add_u32 v17, v206
	s_waitcnt lgkmcnt(7)
	v_sub_f32_e32 v10, v10, v192
	v_mul_f32_e32 v150, v10, v193
	v_cvt_i32_f32_e32 v18, v150
	v_min_i32_e32 v18, 0x3ff, v18
	v_lshl_add_u32 v18, v18, 2, s41
	ds_add_u32 v18, v206
	s_waitcnt lgkmcnt(7)
	v_sub_f32_e32 v11, v11, v192
	v_mul_f32_e32 v151, v11, v193
	v_cvt_i32_f32_e32 v19, v151
	v_min_i32_e32 v19, 0x3ff, v19
	v_lshl_add_u32 v19, v19, 2, s41
	ds_add_u32 v19, v206
	s_waitcnt lgkmcnt(7)
	v_sub_f32_e32 v12, v12, v192
	v_mul_f32_e32 v152, v12, v193
	v_cvt_i32_f32_e32 v20, v152
	v_min_i32_e32 v20, 0x3ff, v20
	v_lshl_add_u32 v20, v20, 2, s41
	ds_add_u32 v20, v206
	s_waitcnt lgkmcnt(7)
	v_sub_f32_e32 v13, v13, v192
	v_mul_f32_e32 v153, v13, v193
	v_cvt_i32_f32_e32 v21, v153
	v_min_i32_e32 v21, 0x3ff, v21
	v_lshl_add_u32 v21, v21, 2, s41
	ds_add_u32 v21, v206
	s_waitcnt lgkmcnt(7)
	v_sub_f32_e32 v14, v14, v192
	v_mul_f32_e32 v154, v14, v193
	v_cvt_i32_f32_e32 v22, v154
	v_min_i32_e32 v22, 0x3ff, v22
	v_lshl_add_u32 v22, v22, 2, s41
	ds_add_u32 v22, v206
	s_waitcnt lgkmcnt(7)
	v_sub_f32_e32 v15, v15, v192
	v_mul_f32_e32 v155, v15, v193
	v_cvt_i32_f32_e32 v23, v155
	v_min_i32_e32 v23, 0x3ff, v23
	v_lshl_add_u32 v23, v23, 2, s41
	ds_add_u32 v23, v206
; DI void selectA_item(const Params& p, int item, int next_item, char* lds, bf16x8 (&qf)[4], float (&wq)[16]) {
;     ...
;     for (int i = 0; i < 64; ++i) { const int idx = gt + 128 * i; const float v = (idx < n) ? scq[idx] : lo; const float u = (v - lo) * scale; uu[i] = u;
;       if (big && idx < n) { int bb = (int)u; bb = bb > 1023 ? 1023 : bb; atomicAdd(&histq[bb], 1); } }
.Lsel_B_5:
	s_cmp_le_u32 s40, 0x1400
	s_cbranch_scc1 .Lsel_B_done
	s_cmp_lt_u32 s40, 0x1800
	s_cbranch_scc1 .Lsel_B_5_part
	ds_read_b32 v8, v181 offset:20480
	ds_read_b32 v9, v181 offset:20992
	ds_read_b32 v10, v181 offset:21504
	ds_read_b32 v11, v181 offset:22016
	ds_read_b32 v12, v181 offset:22528
	ds_read_b32 v13, v181 offset:23040
	ds_read_b32 v14, v181 offset:23552
	ds_read_b32 v15, v181 offset:24064
	s_waitcnt lgkmcnt(7)
	v_sub_f32_e32 v8, v8, v192
	v_mul_f32_e32 v156, v8, v193
	v_cvt_i32_f32_e32 v16, v156
	v_min_i32_e32 v16, 0x3ff, v16
	v_lshl_add_u32 v16, v16, 2, s41
	ds_add_u32 v16, v206
	s_waitcnt lgkmcnt(7)
	v_sub_f32_e32 v9, v9, v192
	v_mul_f32_e32 v157, v9, v193
	v_cvt_i32_f32_e32 v17, v157
	v_min_i32_e32 v17, 0x3ff, v17
	v_lshl_add_u32 v17, v17, 2, s41
	ds_add_u32 v17, v206
	s_waitcnt lgkmcnt(7)
	v_sub_f32_e32 v10, v10, v192
	v_mul_f32_e32 v158, v10, v193
	v_cvt_i32_f32_e32 v18, v158
	v_min_i32_e32 v18, 0x3ff, v18
	v_lshl_add_u32 v18, v18, 2, s41
	ds_add_u32 v18, v206
	s_waitcnt lgkmcnt(7)
	v_sub_f32_e32 v11, v11, v192
	v_mul_f32_e32 v159, v11, v193
	v_cvt_i32_f32_e32 v19, v159
	v_min_i32_e32 v19, 0x3ff, v19
	v_lshl_add_u32 v19, v19, 2, s41
	ds_add_u32 v19, v206
	s_waitcnt lgkmcnt(7)
	v_sub_f32_e32 v12, v12, v192
	v_mul_f32_e32 v160, v12, v193
	v_cvt_i32_f32_e32 v20, v160
	v_min_i32_e32 v20, 0x3ff, v20
	v_lshl_add_u32 v20, v20, 2, s41
	ds_add_u32 v20, v206
	s_waitcnt lgkmcnt(7)
	v_sub_f32_e32 v13, v13, v192
	v_mul_f32_e32 v161, v13, v193
	v_cvt_i32_f32_e32 v21, v161
	v_min_i32_e32 v21, 0x3ff, v21
	v_lshl_add_u32 v21, v21, 2, s41
	ds_add_u32 v21, v206
	s_waitcnt lgkmcnt(7)
	v_sub_f32_e32 v14, v14, v192
	v_mul_f32_e32 v162, v14, v193
	v_cvt_i32_f32_e32 v22, v162
	v_min_i32_e32 v22, 0x3ff, v22
	v_lshl_add_u32 v22, v22, 2, s41
	ds_add_u32 v22, v206
	s_waitcnt lgkmcnt(7)
	v_sub_f32_e32 v15, v15, v192
	v_mul_f32_e32 v163, v15, v193
	v_cvt_i32_f32_e32 v23, v163
	v_min_i32_e32 v23, 0x3ff, v23
	v_lshl_add_u32 v23, v23, 2, s41
	ds_add_u32 v23, v206
.Lsel_B_6:
	s_cmp_le_u32 s40, 0x1800
	s_cbranch_scc1 .Lsel_B_done
	s_cmp_lt_u32 s40, 0x1c00
	s_cbranch_scc1 .Lsel_B_6_part
	ds_read_b32 v8, v181 offset:24576
	ds_read_b32 v9, v181 offset:25088
	ds_read_b32 v10, v181 offset:25600
	ds_read_b32 v11, v181 offset:26112
	ds_read_b32 v12, v181 offset:26624
	ds_read_b32 v13, v181 offset:27136
	ds_read_b32 v14, v181 offset:27648
	ds_read_b32 v15, v181 offset:28160
	s_waitcnt lgkmcnt(7)
	v_sub_f32_e32 v8, v8, v192
	v_mul_f32_e32 v164, v8, v193
	v_cvt_i32_f32_e32 v16, v164
	v_min_i32_e32 v16, 0x3ff, v16
	v_lshl_add_u32 v16, v16, 2, s41
	ds_add_u32 v16, v206
	s_waitcnt lgkmcnt(7)
	v_sub_f32_e32 v9, v9, v192
	v_mul_f32_e32 v165, v9, v193
	v_cvt_i32_f32_e32 v17, v165
	v_min_i32_e32 v17, 0x3ff, v17
	v_lshl_add_u32 v17, v17, 2, s41
	ds_add_u32 v17, v206
	s_waitcnt lgkmcnt(7)
	v_sub_f32_e32 v10, v10, v192
	v_mul_f32_e32 v166, v10, v193
	v_cvt_i32_f32_e32 v18, v166
	v_min_i32_e32 v18, 0x3ff, v18
	v_lshl_add_u32 v18, v18, 2, s41
	ds_add_u32 v18, v206
	s_waitcnt lgkmcnt(7)
	v_sub_f32_e32 v11, v11, v192
	v_mul_f32_e32 v167, v11, v193
	v_cvt_i32_f32_e32 v19, v167
	v_min_i32_e32 v19, 0x3ff, v19
	v_lshl_add_u32 v19, v19, 2, s41
	ds_add_u32 v19, v206
	s_waitcnt lgkmcnt(7)
	v_sub_f32_e32 v12, v12, v192
	v_mul_f32_e32 v168, v12, v193
	v_cvt_i32_f32_e32 v20, v168
	v_min_i32_e32 v20, 0x3ff, v20
	v_lshl_add_u32 v20, v20, 2, s41
	ds_add_u32 v20, v206
	s_waitcnt lgkmcnt(7)
	v_sub_f32_e32 v13, v13, v192
	v_mul_f32_e32 v169, v13, v193
	v_cvt_i32_f32_e32 v21, v169
	v_min_i32_e32 v21, 0x3ff, v21
	v_lshl_add_u32 v21, v21, 2, s41
	ds_add_u32 v21, v206
	s_waitcnt lgkmcnt(7)
	v_sub_f32_e32 v14, v14, v192
	v_mul_f32_e32 v170, v14, v193
	v_cvt_i32_f32_e32 v22, v170
	v_min_i32_e32 v22, 0x3ff, v22
	v_lshl_add_u32 v22, v22, 2, s41
	ds_add_u32 v22, v206
	s_waitcnt lgkmcnt(7)
	v_sub_f32_e32 v15, v15, v192
	v_mul_f32_e32 v171, v15, v193
	v_cvt_i32_f32_e32 v23, v171
	v_min_i32_e32 v23, 0x3ff, v23
	v_lshl_add_u32 v23, v23, 2, s41
	ds_add_u32 v23, v206
.Lsel_B_7:
	s_cmp_le_u32 s40, 0x1c00
	s_cbranch_scc1 .Lsel_B_done
	s_cmp_lt_u32 s40, 0x2000
	s_cbranch_scc1 .Lsel_B_7_part
	ds_read_b32 v8, v181 offset:28672
	ds_read_b32 v9, v181 offset:29184
	ds_read_b32 v10, v181 offset:29696
	ds_read_b32 v11, v181 offset:30208
	ds_read_b32 v12, v181 offset:30720
	ds_read_b32 v13, v181 offset:31232
	ds_read_b32 v14, v181 offset:31744
	ds_read_b32 v15, v181 offset:32256
	s_waitcnt lgkmcnt(7)
	v_sub_f32_e32 v8, v8, v192
	v_mul_f32_e32 v172, v8, v193
	v_cvt_i32_f32_e32 v16, v172
	v_min_i32_e32 v16, 0x3ff, v16
	v_lshl_add_u32 v16, v16, 2, s41
	ds_add_u32 v16, v206
	s_waitcnt lgkmcnt(7)
	v_sub_f32_e32 v9, v9, v192
	v_mul_f32_e32 v173, v9, v193
	v_cvt_i32_f32_e32 v17, v173
	v_min_i32_e32 v17, 0x3ff, v17
	v_lshl_add_u32 v17, v17, 2, s41
	ds_add_u32 v17, v206
	s_waitcnt lgkmcnt(7)
	v_sub_f32_e32 v10, v10, v192
	v_mul_f32_e32 v174, v10, v193
	v_cvt_i32_f32_e32 v18, v174
	v_min_i32_e32 v18, 0x3ff, v18
	v_lshl_add_u32 v18, v18, 2, s41
	ds_add_u32 v18, v206
	s_waitcnt lgkmcnt(7)
	v_sub_f32_e32 v11, v11, v192
	v_mul_f32_e32 v175, v11, v193
	v_cvt_i32_f32_e32 v19, v175
	v_min_i32_e32 v19, 0x3ff, v19
	v_lshl_add_u32 v19, v19, 2, s41
	ds_add_u32 v19, v206
	s_waitcnt lgkmcnt(7)
	v_sub_f32_e32 v12, v12, v192
	v_mul_f32_e32 v176, v12, v193
	v_cvt_i32_f32_e32 v20, v176
	v_min_i32_e32 v20, 0x3ff, v20
	v_lshl_add_u32 v20, v20, 2, s41
	ds_add_u32 v20, v206
	s_waitcnt lgkmcnt(7)
	v_sub_f32_e32 v13, v13, v192
	v_mul_f32_e32 v177, v13, v193
	v_cvt_i32_f32_e32 v21, v177
	v_min_i32_e32 v21, 0x3ff, v21
	v_lshl_add_u32 v21, v21, 2, s41
	ds_add_u32 v21, v206
	s_waitcnt lgkmcnt(7)
	v_sub_f32_e32 v14, v14, v192
	v_mul_f32_e32 v178, v14, v193
	v_cvt_i32_f32_e32 v22, v178
	v_min_i32_e32 v22, 0x3ff, v22
	v_lshl_add_u32 v22, v22, 2, s41
	ds_add_u32 v22, v206
	s_waitcnt lgkmcnt(7)
	v_sub_f32_e32 v15, v15, v192
	v_mul_f32_e32 v179, v15, v193
	v_cvt_i32_f32_e32 v23, v179
	v_min_i32_e32 v23, 0x3ff, v23
	v_lshl_add_u32 v23, v23, 2, s41
	ds_add_u32 v23, v206
	s_branch .Lsel_B_done
; DI void selectA_item(const Params& p, int item, int next_item, char* lds, bf16x8 (&qf)[4], float (&wq)[16]) {
;     ...
;     for (int i = 0; i < 64; ++i) { const int idx = gt + 128 * i; const float v = (idx < n) ? scq[idx] : lo; const float u = (v - lo) * scale; uu[i] = u;
;       if (big && idx < n) { int bb = (int)u; bb = bb > 1023 ? 1023 : bb; atomicAdd(&histq[bb], 1); } }
.Lsel_B_0_part:
	s_mov_b32 s2, s40
	ds_read_b32 v8, v181 offset:0
	ds_read_b32 v9, v181 offset:512
	ds_read_b32 v10, v181 offset:1024
	ds_read_b32 v11, v181 offset:1536
	ds_read_b32 v12, v181 offset:2048
	ds_read_b32 v13, v181 offset:2560
	ds_read_b32 v14, v181 offset:3072
	ds_read_b32 v15, v181 offset:3584
	v_cmp_gt_i32_e64 s[66:67], s2, v180
	s_sub_i32 s3, s2, 0x80
	v_cmp_gt_i32_e64 s[68:69], s3, v180
	s_sub_i32 s3, s2, 0x100
	v_cmp_gt_i32_e64 s[70:71], s3, v180
	s_sub_i32 s3, s2, 0x180
	v_cmp_gt_i32_e64 s[72:73], s3, v180
	s_sub_i32 s3, s2, 0x200
	v_cmp_gt_i32_e64 s[74:75], s3, v180
	s_sub_i32 s3, s2, 0x280
	v_cmp_gt_i32_e64 s[76:77], s3, v180
	s_sub_i32 s3, s2, 0x300
	v_cmp_gt_i32_e64 s[78:79], s3, v180
	s_sub_i32 s3, s2, 0x380
	v_cmp_gt_i32_e64 s[80:81], s3, v180
	s_waitcnt lgkmcnt(7)
	v_sub_f32_e32 v8, v8, v192
	v_mul_f32_e32 v8, v8, v193
	v_cndmask_b32_e64 v116, -1.0, v8, s[66:67]
	v_cvt_i32_f32_e32 v16, v116
	v_min_i32_e32 v16, 0x3ff, v16
	v_lshl_add_u32 v16, v16, 2, s41
	v_cndmask_b32_e64 v16, v205, v16, s[66:67]
	ds_add_u32 v16, v206
	s_waitcnt lgkmcnt(7)
	v_sub_f32_e32 v9, v9, v192
	v_mul_f32_e32 v9, v9, v193
	v_cndmask_b32_e64 v117, -1.0, v9, s[68:69]
	v_cvt_i32_f32_e32 v17, v117
	v_min_i32_e32 v17, 0x3ff, v17
	v_lshl_add_u32 v17, v17, 2, s41
	v_cndmask_b32_e64 v17, v205, v17, s[68:69]
	ds_add_u32 v17, v206
	s_waitcnt lgkmcnt(7)
	v_sub_f32_e32 v10, v10, v192
	v_mul_f32_e32 v10, v10, v193
	v_cndmask_b32_e64 v118, -1.0, v10, s[70:71]
	v_cvt_i32_f32_e32 v18, v118
	v_min_i32_e32 v18, 0x3ff, v18
	v_lshl_add_u32 v18, v18, 2, s41
	v_cndmask_b32_e64 v18, v205, v18, s[70:71]
	ds_add_u32 v18, v206
	s_waitcnt lgkmcnt(7)
	v_sub_f32_e32 v11, v11, v192
	v_mul_f32_e32 v11, v11, v193
	v_cndmask_b32_e64 v119, -1.0, v11, s[72:73]
	v_cvt_i32_f32_e32 v19, v119
	v_min_i32_e32 v19, 0x3ff, v19
	v_lshl_add_u32 v19, v19, 2, s41
	v_cndmask_b32_e64 v19, v205, v19, s[72:73]
	ds_add_u32 v19, v206
	s_waitcnt lgkmcnt(7)
	v_sub_f32_e32 v12, v12, v192
	v_mul_f32_e32 v12, v12, v193
	v_cndmask_b32_e64 v120, -1.0, v12, s[74:75]
	v_cvt_i32_f32_e32 v20, v120
	v_min_i32_e32 v20, 0x3ff, v20
	v_lshl_add_u32 v20, v20, 2, s41
	v_cndmask_b32_e64 v20, v205, v20, s[74:75]
	ds_add_u32 v20, v206
	s_waitcnt lgkmcnt(7)
	v_sub_f32_e32 v13, v13, v192
	v_mul_f32_e32 v13, v13, v193
	v_cndmask_b32_e64 v121, -1.0, v13, s[76:77]
	v_cvt_i32_f32_e32 v21, v121
	v_min_i32_e32 v21, 0x3ff, v21
	v_lshl_add_u32 v21, v21, 2, s41
	v_cndmask_b32_e64 v21, v205, v21, s[76:77]
	ds_add_u32 v21, v206
	s_waitcnt lgkmcnt(7)
	v_sub_f32_e32 v14, v14, v192
	v_mul_f32_e32 v14, v14, v193
	v_cndmask_b32_e64 v122, -1.0, v14, s[78:79]
	v_cvt_i32_f32_e32 v22, v122
	v_min_i32_e32 v22, 0x3ff, v22
	v_lshl_add_u32 v22, v22, 2, s41
	v_cndmask_b32_e64 v22, v205, v22, s[78:79]
	ds_add_u32 v22, v206
	s_waitcnt lgkmcnt(7)
	v_sub_f32_e32 v15, v15, v192
	v_mul_f32_e32 v15, v15, v193
	v_cndmask_b32_e64 v123, -1.0, v15, s[80:81]
	v_cvt_i32_f32_e32 v23, v123
	v_min_i32_e32 v23, 0x3ff, v23
	v_lshl_add_u32 v23, v23, 2, s41
	v_cndmask_b32_e64 v23, v205, v23, s[80:81]
	ds_add_u32 v23, v206
	s_branch .Lsel_B_done
.Lsel_B_1_part:
	s_sub_i32 s2, s40, 0x400
	ds_read_b32 v8, v181 offset:4096
	ds_read_b32 v9, v181 offset:4608
	ds_read_b32 v10, v181 offset:5120
	ds_read_b32 v11, v181 offset:5632
	ds_read_b32 v12, v181 offset:6144
	ds_read_b32 v13, v181 offset:6656
	ds_read_b32 v14, v181 offset:7168
	ds_read_b32 v15, v181 offset:7680
	v_cmp_gt_i32_e64 s[66:67], s2, v180
	s_sub_i32 s3, s2, 0x80
	v_cmp_gt_i32_e64 s[68:69], s3, v180
	s_sub_i32 s3, s2, 0x100
	v_cmp_gt_i32_e64 s[70:71], s3, v180
	s_sub_i32 s3, s2, 0x180
	v_cmp_gt_i32_e64 s[72:73], s3, v180
	s_sub_i32 s3, s2, 0x200
	v_cmp_gt_i32_e64 s[74:75], s3, v180
	s_sub_i32 s3, s2, 0x280
	v_cmp_gt_i32_e64 s[76:77], s3, v180
	s_sub_i32 s3, s2, 0x300
	v_cmp_gt_i32_e64 s[78:79], s3, v180
	s_sub_i32 s3, s2, 0x380
	v_cmp_gt_i32_e64 s[80:81], s3, v180
	s_waitcnt lgkmcnt(7)
	v_sub_f32_e32 v8, v8, v192
	v_mul_f32_e32 v8, v8, v193
	v_cndmask_b32_e64 v124, -1.0, v8, s[66:67]
	v_cvt_i32_f32_e32 v16, v124
	v_min_i32_e32 v16, 0x3ff, v16
	v_lshl_add_u32 v16, v16, 2, s41
	v_cndmask_b32_e64 v16, v205, v16, s[66:67]
	ds_add_u32 v16, v206
	s_waitcnt lgkmcnt(7)
	v_sub_f32_e32 v9, v9, v192
	v_mul_f32_e32 v9, v9, v193
	v_cndmask_b32_e64 v125, -1.0, v9, s[68:69]
	v_cvt_i32_f32_e32 v17, v125
	v_min_i32_e32 v17, 0x3ff, v17
	v_lshl_add_u32 v17, v17, 2, s41
	v_cndmask_b32_e64 v17, v205, v17, s[68:69]
	ds_add_u32 v17, v206
	s_waitcnt lgkmcnt(7)
	v_sub_f32_e32 v10, v10, v192
	v_mul_f32_e32 v10, v10, v193
	v_cndmask_b32_e64 v126, -1.0, v10, s[70:71]
	v_cvt_i32_f32_e32 v18, v126
	v_min_i32_e32 v18, 0x3ff, v18
	v_lshl_add_u32 v18, v18, 2, s41
	v_cndmask_b32_e64 v18, v205, v18, s[70:71]
	ds_add_u32 v18, v206
	s_waitcnt lgkmcnt(7)
	v_sub_f32_e32 v11, v11, v192
	v_mul_f32_e32 v11, v11, v193
	v_cndmask_b32_e64 v127, -1.0, v11, s[72:73]
	v_cvt_i32_f32_e32 v19, v127
	v_min_i32_e32 v19, 0x3ff, v19
	v_lshl_add_u32 v19, v19, 2, s41
	v_cndmask_b32_e64 v19, v205, v19, s[72:73]
	ds_add_u32 v19, v206
	s_waitcnt lgkmcnt(7)
	v_sub_f32_e32 v12, v12, v192
	v_mul_f32_e32 v12, v12, v193
	v_cndmask_b32_e64 v128, -1.0, v12, s[74:75]
	v_cvt_i32_f32_e32 v20, v128
	v_min_i32_e32 v20, 0x3ff, v20
	v_lshl_add_u32 v20, v20, 2, s41
	v_cndmask_b32_e64 v20, v205, v20, s[74:75]
	ds_add_u32 v20, v206
	s_waitcnt lgkmcnt(7)
	v_sub_f32_e32 v13, v13, v192
	v_mul_f32_e32 v13, v13, v193
	v_cndmask_b32_e64 v129, -1.0, v13, s[76:77]
	v_cvt_i32_f32_e32 v21, v129
	v_min_i32_e32 v21, 0x3ff, v21
	v_lshl_add_u32 v21, v21, 2, s41
	v_cndmask_b32_e64 v21, v205, v21, s[76:77]
	ds_add_u32 v21, v206
	s_waitcnt lgkmcnt(7)
	v_sub_f32_e32 v14, v14, v192
	v_mul_f32_e32 v14, v14, v193
	v_cndmask_b32_e64 v130, -1.0, v14, s[78:79]
	v_cvt_i32_f32_e32 v22, v130
	v_min_i32_e32 v22, 0x3ff, v22
	v_lshl_add_u32 v22, v22, 2, s41
	v_cndmask_b32_e64 v22, v205, v22, s[78:79]
	ds_add_u32 v22, v206
	s_waitcnt lgkmcnt(7)
	v_sub_f32_e32 v15, v15, v192
	v_mul_f32_e32 v15, v15, v193
	v_cndmask_b32_e64 v131, -1.0, v15, s[80:81]
	v_cvt_i32_f32_e32 v23, v131
	v_min_i32_e32 v23, 0x3ff, v23
	v_lshl_add_u32 v23, v23, 2, s41
	v_cndmask_b32_e64 v23, v205, v23, s[80:81]
	ds_add_u32 v23, v206
	s_branch .Lsel_B_done
; DI void selectA_item(const Params& p, int item, int next_item, char* lds, bf16x8 (&qf)[4], float (&wq)[16]) {
;     ...
;     for (int i = 0; i < 64; ++i) { const int idx = gt + 128 * i; const float v = (idx < n) ? scq[idx] : lo; const float u = (v - lo) * scale; uu[i] = u;
;       if (big && idx < n) { int bb = (int)u; bb = bb > 1023 ? 1023 : bb; atomicAdd(&histq[bb], 1); } }
.Lsel_B_2_part:
	s_sub_i32 s2, s40, 0x800
	ds_read_b32 v8, v181 offset:8192
	ds_read_b32 v9, v181 offset:8704
	ds_read_b32 v10, v181 offset:9216
	ds_read_b32 v11, v181 offset:9728
	ds_read_b32 v12, v181 offset:10240
	ds_read_b32 v13, v181 offset:10752
	ds_read_b32 v14, v181 offset:11264
	ds_read_b32 v15, v181 offset:11776
	v_cmp_gt_i32_e64 s[66:67], s2, v180
	s_sub_i32 s3, s2, 0x80
	v_cmp_gt_i32_e64 s[68:69], s3, v180
	s_sub_i32 s3, s2, 0x100
	v_cmp_gt_i32_e64 s[70:71], s3, v180
	s_sub_i32 s3, s2, 0x180
	v_cmp_gt_i32_e64 s[72:73], s3, v180
	s_sub_i32 s3, s2, 0x200
	v_cmp_gt_i32_e64 s[74:75], s3, v180
	s_sub_i32 s3, s2, 0x280
	v_cmp_gt_i32_e64 s[76:77], s3, v180
	s_sub_i32 s3, s2, 0x300
	v_cmp_gt_i32_e64 s[78:79], s3, v180
	s_sub_i32 s3, s2, 0x380
	v_cmp_gt_i32_e64 s[80:81], s3, v180
	s_waitcnt lgkmcnt(7)
	v_sub_f32_e32 v8, v8, v192
	v_mul_f32_e32 v8, v8, v193
	v_cndmask_b32_e64 v132, -1.0, v8, s[66:67]
	v_cvt_i32_f32_e32 v16, v132
	v_min_i32_e32 v16, 0x3ff, v16
	v_lshl_add_u32 v16, v16, 2, s41
	v_cndmask_b32_e64 v16, v205, v16, s[66:67]
	ds_add_u32 v16, v206
	s_waitcnt lgkmcnt(7)
	v_sub_f32_e32 v9, v9, v192
	v_mul_f32_e32 v9, v9, v193
	v_cndmask_b32_e64 v133, -1.0, v9, s[68:69]
	v_cvt_i32_f32_e32 v17, v133
	v_min_i32_e32 v17, 0x3ff, v17
	v_lshl_add_u32 v17, v17, 2, s41
	v_cndmask_b32_e64 v17, v205, v17, s[68:69]
	ds_add_u32 v17, v206
	s_waitcnt lgkmcnt(7)
	v_sub_f32_e32 v10, v10, v192
	v_mul_f32_e32 v10, v10, v193
	v_cndmask_b32_e64 v134, -1.0, v10, s[70:71]
	v_cvt_i32_f32_e32 v18, v134
	v_min_i32_e32 v18, 0x3ff, v18
	v_lshl_add_u32 v18, v18, 2, s41
	v_cndmask_b32_e64 v18, v205, v18, s[70:71]
	ds_add_u32 v18, v206
	s_waitcnt lgkmcnt(7)
	v_sub_f32_e32 v11, v11, v192
	v_mul_f32_e32 v11, v11, v193
	v_cndmask_b32_e64 v135, -1.0, v11, s[72:73]
	v_cvt_i32_f32_e32 v19, v135
	v_min_i32_e32 v19, 0x3ff, v19
	v_lshl_add_u32 v19, v19, 2, s41
	v_cndmask_b32_e64 v19, v205, v19, s[72:73]
	ds_add_u32 v19, v206
	s_waitcnt lgkmcnt(7)
	v_sub_f32_e32 v12, v12, v192
	v_mul_f32_e32 v12, v12, v193
	v_cndmask_b32_e64 v136, -1.0, v12, s[74:75]
	v_cvt_i32_f32_e32 v20, v136
	v_min_i32_e32 v20, 0x3ff, v20
	v_lshl_add_u32 v20, v20, 2, s41
	v_cndmask_b32_e64 v20, v205, v20, s[74:75]
	ds_add_u32 v20, v206
	s_waitcnt lgkmcnt(7)
	v_sub_f32_e32 v13, v13, v192
	v_mul_f32_e32 v13, v13, v193
	v_cndmask_b32_e64 v137, -1.0, v13, s[76:77]
	v_cvt_i32_f32_e32 v21, v137
	v_min_i32_e32 v21, 0x3ff, v21
	v_lshl_add_u32 v21, v21, 2, s41
	v_cndmask_b32_e64 v21, v205, v21, s[76:77]
	ds_add_u32 v21, v206
	s_waitcnt lgkmcnt(7)
	v_sub_f32_e32 v14, v14, v192
	v_mul_f32_e32 v14, v14, v193
	v_cndmask_b32_e64 v138, -1.0, v14, s[78:79]
	v_cvt_i32_f32_e32 v22, v138
	v_min_i32_e32 v22, 0x3ff, v22
	v_lshl_add_u32 v22, v22, 2, s41
	v_cndmask_b32_e64 v22, v205, v22, s[78:79]
	ds_add_u32 v22, v206
	s_waitcnt lgkmcnt(7)
	v_sub_f32_e32 v15, v15, v192
	v_mul_f32_e32 v15, v15, v193
	v_cndmask_b32_e64 v139, -1.0, v15, s[80:81]
	v_cvt_i32_f32_e32 v23, v139
	v_min_i32_e32 v23, 0x3ff, v23
	v_lshl_add_u32 v23, v23, 2, s41
	v_cndmask_b32_e64 v23, v205, v23, s[80:81]
	ds_add_u32 v23, v206
	s_branch .Lsel_B_done
.Lsel_B_3_part:
	s_sub_i32 s2, s40, 0xc00
	ds_read_b32 v8, v181 offset:12288
	ds_read_b32 v9, v181 offset:12800
	ds_read_b32 v10, v181 offset:13312
	ds_read_b32 v11, v181 offset:13824
	ds_read_b32 v12, v181 offset:14336
	ds_read_b32 v13, v181 offset:14848
	ds_read_b32 v14, v181 offset:15360
	ds_read_b32 v15, v181 offset:15872
	v_cmp_gt_i32_e64 s[66:67], s2, v180
	s_sub_i32 s3, s2, 0x80
	v_cmp_gt_i32_e64 s[68:69], s3, v180
	s_sub_i32 s3, s2, 0x100
	v_cmp_gt_i32_e64 s[70:71], s3, v180
	s_sub_i32 s3, s2, 0x180
	v_cmp_gt_i32_e64 s[72:73], s3, v180
	s_sub_i32 s3, s2, 0x200
	v_cmp_gt_i32_e64 s[74:75], s3, v180
	s_sub_i32 s3, s2, 0x280
	v_cmp_gt_i32_e64 s[76:77], s3, v180
	s_sub_i32 s3, s2, 0x300
	v_cmp_gt_i32_e64 s[78:79], s3, v180
	s_sub_i32 s3, s2, 0x380
	v_cmp_gt_i32_e64 s[80:81], s3, v180
	s_waitcnt lgkmcnt(7)
	v_sub_f32_e32 v8, v8, v192
	v_mul_f32_e32 v8, v8, v193
	v_cndmask_b32_e64 v140, -1.0, v8, s[66:67]
	v_cvt_i32_f32_e32 v16, v140
	v_min_i32_e32 v16, 0x3ff, v16
	v_lshl_add_u32 v16, v16, 2, s41
	v_cndmask_b32_e64 v16, v205, v16, s[66:67]
	ds_add_u32 v16, v206
	s_waitcnt lgkmcnt(7)
	v_sub_f32_e32 v9, v9, v192
	v_mul_f32_e32 v9, v9, v193
	v_cndmask_b32_e64 v141, -1.0, v9, s[68:69]
	v_cvt_i32_f32_e32 v17, v141
	v_min_i32_e32 v17, 0x3ff, v17
	v_lshl_add_u32 v17, v17, 2, s41
	v_cndmask_b32_e64 v17, v205, v17, s[68:69]
	ds_add_u32 v17, v206
	s_waitcnt lgkmcnt(7)
	v_sub_f32_e32 v10, v10, v192
	v_mul_f32_e32 v10, v10, v193
	v_cndmask_b32_e64 v142, -1.0, v10, s[70:71]
	v_cvt_i32_f32_e32 v18, v142
	v_min_i32_e32 v18, 0x3ff, v18
	v_lshl_add_u32 v18, v18, 2, s41
	v_cndmask_b32_e64 v18, v205, v18, s[70:71]
	ds_add_u32 v18, v206
	s_waitcnt lgkmcnt(7)
	v_sub_f32_e32 v11, v11, v192
	v_mul_f32_e32 v11, v11, v193
	v_cndmask_b32_e64 v143, -1.0, v11, s[72:73]
	v_cvt_i32_f32_e32 v19, v143
	v_min_i32_e32 v19, 0x3ff, v19
	v_lshl_add_u32 v19, v19, 2, s41
	v_cndmask_b32_e64 v19, v205, v19, s[72:73]
	ds_add_u32 v19, v206
	s_waitcnt lgkmcnt(7)
	v_sub_f32_e32 v12, v12, v192
	v_mul_f32_e32 v12, v12, v193
	v_cndmask_b32_e64 v144, -1.0, v12, s[74:75]
	v_cvt_i32_f32_e32 v20, v144
	v_min_i32_e32 v20, 0x3ff, v20
	v_lshl_add_u32 v20, v20, 2, s41
	v_cndmask_b32_e64 v20, v205, v20, s[74:75]
	ds_add_u32 v20, v206
	s_waitcnt lgkmcnt(7)
	v_sub_f32_e32 v13, v13, v192
	v_mul_f32_e32 v13, v13, v193
	v_cndmask_b32_e64 v145, -1.0, v13, s[76:77]
	v_cvt_i32_f32_e32 v21, v145
	v_min_i32_e32 v21, 0x3ff, v21
	v_lshl_add_u32 v21, v21, 2, s41
	v_cndmask_b32_e64 v21, v205, v21, s[76:77]
	ds_add_u32 v21, v206
	s_waitcnt lgkmcnt(7)
	v_sub_f32_e32 v14, v14, v192
	v_mul_f32_e32 v14, v14, v193
	v_cndmask_b32_e64 v146, -1.0, v14, s[78:79]
	v_cvt_i32_f32_e32 v22, v146
	v_min_i32_e32 v22, 0x3ff, v22
	v_lshl_add_u32 v22, v22, 2, s41
	v_cndmask_b32_e64 v22, v205, v22, s[78:79]
	ds_add_u32 v22, v206
	s_waitcnt lgkmcnt(7)
	v_sub_f32_e32 v15, v15, v192
	v_mul_f32_e32 v15, v15, v193
	v_cndmask_b32_e64 v147, -1.0, v15, s[80:81]
	v_cvt_i32_f32_e32 v23, v147
	v_min_i32_e32 v23, 0x3ff, v23
	v_lshl_add_u32 v23, v23, 2, s41
	v_cndmask_b32_e64 v23, v205, v23, s[80:81]
	ds_add_u32 v23, v206
	s_branch .Lsel_B_done
; DI void selectA_item(const Params& p, int item, int next_item, char* lds, bf16x8 (&qf)[4], float (&wq)[16]) {
;     ...
;     for (int i = 0; i < 64; ++i) { const int idx = gt + 128 * i; const float v = (idx < n) ? scq[idx] : lo; const float u = (v - lo) * scale; uu[i] = u;
;       if (big && idx < n) { int bb = (int)u; bb = bb > 1023 ? 1023 : bb; atomicAdd(&histq[bb], 1); } }
.Lsel_B_4_part:
	s_sub_i32 s2, s40, 0x1000
	ds_read_b32 v8, v181 offset:16384
	ds_read_b32 v9, v181 offset:16896
	ds_read_b32 v10, v181 offset:17408
	ds_read_b32 v11, v181 offset:17920
	ds_read_b32 v12, v181 offset:18432
	ds_read_b32 v13, v181 offset:18944
	ds_read_b32 v14, v181 offset:19456
	ds_read_b32 v15, v181 offset:19968
	v_cmp_gt_i32_e64 s[66:67], s2, v180
	s_sub_i32 s3, s2, 0x80
	v_cmp_gt_i32_e64 s[68:69], s3, v180
	s_sub_i32 s3, s2, 0x100
	v_cmp_gt_i32_e64 s[70:71], s3, v180
	s_sub_i32 s3, s2, 0x180
	v_cmp_gt_i32_e64 s[72:73], s3, v180
	s_sub_i32 s3, s2, 0x200
	v_cmp_gt_i32_e64 s[74:75], s3, v180
	s_sub_i32 s3, s2, 0x280
	v_cmp_gt_i32_e64 s[76:77], s3, v180
	s_sub_i32 s3, s2, 0x300
	v_cmp_gt_i32_e64 s[78:79], s3, v180
	s_sub_i32 s3, s2, 0x380
	v_cmp_gt_i32_e64 s[80:81], s3, v180
	s_waitcnt lgkmcnt(7)
	v_sub_f32_e32 v8, v8, v192
	v_mul_f32_e32 v8, v8, v193
	v_cndmask_b32_e64 v148, -1.0, v8, s[66:67]
	v_cvt_i32_f32_e32 v16, v148
	v_min_i32_e32 v16, 0x3ff, v16
	v_lshl_add_u32 v16, v16, 2, s41
	v_cndmask_b32_e64 v16, v205, v16, s[66:67]
	ds_add_u32 v16, v206
	s_waitcnt lgkmcnt(7)
	v_sub_f32_e32 v9, v9, v192
	v_mul_f32_e32 v9, v9, v193
	v_cndmask_b32_e64 v149, -1.0, v9, s[68:69]
	v_cvt_i32_f32_e32 v17, v149
	v_min_i32_e32 v17, 0x3ff, v17
	v_lshl_add_u32 v17, v17, 2, s41
	v_cndmask_b32_e64 v17, v205, v17, s[68:69]
	ds_add_u32 v17, v206
	s_waitcnt lgkmcnt(7)
	v_sub_f32_e32 v10, v10, v192
	v_mul_f32_e32 v10, v10, v193
	v_cndmask_b32_e64 v150, -1.0, v10, s[70:71]
	v_cvt_i32_f32_e32 v18, v150
	v_min_i32_e32 v18, 0x3ff, v18
	v_lshl_add_u32 v18, v18, 2, s41
	v_cndmask_b32_e64 v18, v205, v18, s[70:71]
	ds_add_u32 v18, v206
	s_waitcnt lgkmcnt(7)
	v_sub_f32_e32 v11, v11, v192
	v_mul_f32_e32 v11, v11, v193
	v_cndmask_b32_e64 v151, -1.0, v11, s[72:73]
	v_cvt_i32_f32_e32 v19, v151
	v_min_i32_e32 v19, 0x3ff, v19
	v_lshl_add_u32 v19, v19, 2, s41
	v_cndmask_b32_e64 v19, v205, v19, s[72:73]
	ds_add_u32 v19, v206
	s_waitcnt lgkmcnt(7)
	v_sub_f32_e32 v12, v12, v192
	v_mul_f32_e32 v12, v12, v193
	v_cndmask_b32_e64 v152, -1.0, v12, s[74:75]
	v_cvt_i32_f32_e32 v20, v152
	v_min_i32_e32 v20, 0x3ff, v20
	v_lshl_add_u32 v20, v20, 2, s41
	v_cndmask_b32_e64 v20, v205, v20, s[74:75]
	ds_add_u32 v20, v206
	s_waitcnt lgkmcnt(7)
	v_sub_f32_e32 v13, v13, v192
	v_mul_f32_e32 v13, v13, v193
	v_cndmask_b32_e64 v153, -1.0, v13, s[76:77]
	v_cvt_i32_f32_e32 v21, v153
	v_min_i32_e32 v21, 0x3ff, v21
	v_lshl_add_u32 v21, v21, 2, s41
	v_cndmask_b32_e64 v21, v205, v21, s[76:77]
	ds_add_u32 v21, v206
	s_waitcnt lgkmcnt(7)
	v_sub_f32_e32 v14, v14, v192
	v_mul_f32_e32 v14, v14, v193
	v_cndmask_b32_e64 v154, -1.0, v14, s[78:79]
	v_cvt_i32_f32_e32 v22, v154
	v_min_i32_e32 v22, 0x3ff, v22
	v_lshl_add_u32 v22, v22, 2, s41
	v_cndmask_b32_e64 v22, v205, v22, s[78:79]
	ds_add_u32 v22, v206
	s_waitcnt lgkmcnt(7)
	v_sub_f32_e32 v15, v15, v192
	v_mul_f32_e32 v15, v15, v193
	v_cndmask_b32_e64 v155, -1.0, v15, s[80:81]
	v_cvt_i32_f32_e32 v23, v155
	v_min_i32_e32 v23, 0x3ff, v23
	v_lshl_add_u32 v23, v23, 2, s41
	v_cndmask_b32_e64 v23, v205, v23, s[80:81]
	ds_add_u32 v23, v206
	s_branch .Lsel_B_done
.Lsel_B_5_part:
	s_sub_i32 s2, s40, 0x1400
	ds_read_b32 v8, v181 offset:20480
	ds_read_b32 v9, v181 offset:20992
	ds_read_b32 v10, v181 offset:21504
	ds_read_b32 v11, v181 offset:22016
	ds_read_b32 v12, v181 offset:22528
	ds_read_b32 v13, v181 offset:23040
	ds_read_b32 v14, v181 offset:23552
	ds_read_b32 v15, v181 offset:24064
	v_cmp_gt_i32_e64 s[66:67], s2, v180
	s_sub_i32 s3, s2, 0x80
	v_cmp_gt_i32_e64 s[68:69], s3, v180
	s_sub_i32 s3, s2, 0x100
	v_cmp_gt_i32_e64 s[70:71], s3, v180
	s_sub_i32 s3, s2, 0x180
	v_cmp_gt_i32_e64 s[72:73], s3, v180
	s_sub_i32 s3, s2, 0x200
	v_cmp_gt_i32_e64 s[74:75], s3, v180
	s_sub_i32 s3, s2, 0x280
	v_cmp_gt_i32_e64 s[76:77], s3, v180
	s_sub_i32 s3, s2, 0x300
	v_cmp_gt_i32_e64 s[78:79], s3, v180
	s_sub_i32 s3, s2, 0x380
	v_cmp_gt_i32_e64 s[80:81], s3, v180
	s_waitcnt lgkmcnt(7)
	v_sub_f32_e32 v8, v8, v192
	v_mul_f32_e32 v8, v8, v193
	v_cndmask_b32_e64 v156, -1.0, v8, s[66:67]
	v_cvt_i32_f32_e32 v16, v156
	v_min_i32_e32 v16, 0x3ff, v16
	v_lshl_add_u32 v16, v16, 2, s41
	v_cndmask_b32_e64 v16, v205, v16, s[66:67]
	ds_add_u32 v16, v206
	s_waitcnt lgkmcnt(7)
	v_sub_f32_e32 v9, v9, v192
	v_mul_f32_e32 v9, v9, v193
	v_cndmask_b32_e64 v157, -1.0, v9, s[68:69]
	v_cvt_i32_f32_e32 v17, v157
	v_min_i32_e32 v17, 0x3ff, v17
	v_lshl_add_u32 v17, v17, 2, s41
	v_cndmask_b32_e64 v17, v205, v17, s[68:69]
	ds_add_u32 v17, v206
	s_waitcnt lgkmcnt(7)
	v_sub_f32_e32 v10, v10, v192
	v_mul_f32_e32 v10, v10, v193
	v_cndmask_b32_e64 v158, -1.0, v10, s[70:71]
	v_cvt_i32_f32_e32 v18, v158
	v_min_i32_e32 v18, 0x3ff, v18
	v_lshl_add_u32 v18, v18, 2, s41
	v_cndmask_b32_e64 v18, v205, v18, s[70:71]
	ds_add_u32 v18, v206
	s_waitcnt lgkmcnt(7)
	v_sub_f32_e32 v11, v11, v192
	v_mul_f32_e32 v11, v11, v193
	v_cndmask_b32_e64 v159, -1.0, v11, s[72:73]
	v_cvt_i32_f32_e32 v19, v159
	v_min_i32_e32 v19, 0x3ff, v19
	v_lshl_add_u32 v19, v19, 2, s41
	v_cndmask_b32_e64 v19, v205, v19, s[72:73]
	ds_add_u32 v19, v206
	s_waitcnt lgkmcnt(7)
	v_sub_f32_e32 v12, v12, v192
	v_mul_f32_e32 v12, v12, v193
	v_cndmask_b32_e64 v160, -1.0, v12, s[74:75]
	v_cvt_i32_f32_e32 v20, v160
	v_min_i32_e32 v20, 0x3ff, v20
	v_lshl_add_u32 v20, v20, 2, s41
	v_cndmask_b32_e64 v20, v205, v20, s[74:75]
	ds_add_u32 v20, v206
	s_waitcnt lgkmcnt(7)
	v_sub_f32_e32 v13, v13, v192
	v_mul_f32_e32 v13, v13, v193
	v_cndmask_b32_e64 v161, -1.0, v13, s[76:77]
	v_cvt_i32_f32_e32 v21, v161
	v_min_i32_e32 v21, 0x3ff, v21
	v_lshl_add_u32 v21, v21, 2, s41
	v_cndmask_b32_e64 v21, v205, v21, s[76:77]
	ds_add_u32 v21, v206
	s_waitcnt lgkmcnt(7)
	v_sub_f32_e32 v14, v14, v192
	v_mul_f32_e32 v14, v14, v193
	v_cndmask_b32_e64 v162, -1.0, v14, s[78:79]
	v_cvt_i32_f32_e32 v22, v162
	v_min_i32_e32 v22, 0x3ff, v22
	v_lshl_add_u32 v22, v22, 2, s41
	v_cndmask_b32_e64 v22, v205, v22, s[78:79]
	ds_add_u32 v22, v206
	s_waitcnt lgkmcnt(7)
	v_sub_f32_e32 v15, v15, v192
	v_mul_f32_e32 v15, v15, v193
	v_cndmask_b32_e64 v163, -1.0, v15, s[80:81]
	v_cvt_i32_f32_e32 v23, v163
	v_min_i32_e32 v23, 0x3ff, v23
	v_lshl_add_u32 v23, v23, 2, s41
	v_cndmask_b32_e64 v23, v205, v23, s[80:81]
	ds_add_u32 v23, v206
	s_branch .Lsel_B_done
; DI void selectA_item(const Params& p, int item, int next_item, char* lds, bf16x8 (&qf)[4], float (&wq)[16]) {
;     ...
;     for (int i = 0; i < 64; ++i) { const int idx = gt + 128 * i; const float v = (idx < n) ? scq[idx] : lo; const float u = (v - lo) * scale; uu[i] = u;
;       if (big && idx < n) { int bb = (int)u; bb = bb > 1023 ? 1023 : bb; atomicAdd(&histq[bb], 1); } }
.Lsel_B_6_part:
	s_sub_i32 s2, s40, 0x1800
	ds_read_b32 v8, v181 offset:24576
	ds_read_b32 v9, v181 offset:25088
	ds_read_b32 v10, v181 offset:25600
	ds_read_b32 v11, v181 offset:26112
	ds_read_b32 v12, v181 offset:26624
	ds_read_b32 v13, v181 offset:27136
	ds_read_b32 v14, v181 offset:27648
	ds_read_b32 v15, v181 offset:28160
	v_cmp_gt_i32_e64 s[66:67], s2, v180
	s_sub_i32 s3, s2, 0x80
	v_cmp_gt_i32_e64 s[68:69], s3, v180
	s_sub_i32 s3, s2, 0x100
	v_cmp_gt_i32_e64 s[70:71], s3, v180
	s_sub_i32 s3, s2, 0x180
	v_cmp_gt_i32_e64 s[72:73], s3, v180
	s_sub_i32 s3, s2, 0x200
	v_cmp_gt_i32_e64 s[74:75], s3, v180
	s_sub_i32 s3, s2, 0x280
	v_cmp_gt_i32_e64 s[76:77], s3, v180
	s_sub_i32 s3, s2, 0x300
	v_cmp_gt_i32_e64 s[78:79], s3, v180
	s_sub_i32 s3, s2, 0x380
	v_cmp_gt_i32_e64 s[80:81], s3, v180
	s_waitcnt lgkmcnt(7)
	v_sub_f32_e32 v8, v8, v192
	v_mul_f32_e32 v8, v8, v193
	v_cndmask_b32_e64 v164, -1.0, v8, s[66:67]
	v_cvt_i32_f32_e32 v16, v164
	v_min_i32_e32 v16, 0x3ff, v16
	v_lshl_add_u32 v16, v16, 2, s41
	v_cndmask_b32_e64 v16, v205, v16, s[66:67]
	ds_add_u32 v16, v206
	s_waitcnt lgkmcnt(7)
	v_sub_f32_e32 v9, v9, v192
	v_mul_f32_e32 v9, v9, v193
	v_cndmask_b32_e64 v165, -1.0, v9, s[68:69]
	v_cvt_i32_f32_e32 v17, v165
	v_min_i32_e32 v17, 0x3ff, v17
	v_lshl_add_u32 v17, v17, 2, s41
	v_cndmask_b32_e64 v17, v205, v17, s[68:69]
	ds_add_u32 v17, v206
	s_waitcnt lgkmcnt(7)
	v_sub_f32_e32 v10, v10, v192
	v_mul_f32_e32 v10, v10, v193
	v_cndmask_b32_e64 v166, -1.0, v10, s[70:71]
	v_cvt_i32_f32_e32 v18, v166
	v_min_i32_e32 v18, 0x3ff, v18
	v_lshl_add_u32 v18, v18, 2, s41
	v_cndmask_b32_e64 v18, v205, v18, s[70:71]
	ds_add_u32 v18, v206
	s_waitcnt lgkmcnt(7)
	v_sub_f32_e32 v11, v11, v192
	v_mul_f32_e32 v11, v11, v193
	v_cndmask_b32_e64 v167, -1.0, v11, s[72:73]
	v_cvt_i32_f32_e32 v19, v167
	v_min_i32_e32 v19, 0x3ff, v19
	v_lshl_add_u32 v19, v19, 2, s41
	v_cndmask_b32_e64 v19, v205, v19, s[72:73]
	ds_add_u32 v19, v206
	s_waitcnt lgkmcnt(7)
	v_sub_f32_e32 v12, v12, v192
	v_mul_f32_e32 v12, v12, v193
	v_cndmask_b32_e64 v168, -1.0, v12, s[74:75]
	v_cvt_i32_f32_e32 v20, v168
	v_min_i32_e32 v20, 0x3ff, v20
	v_lshl_add_u32 v20, v20, 2, s41
	v_cndmask_b32_e64 v20, v205, v20, s[74:75]
	ds_add_u32 v20, v206
	s_waitcnt lgkmcnt(7)
	v_sub_f32_e32 v13, v13, v192
	v_mul_f32_e32 v13, v13, v193
	v_cndmask_b32_e64 v169, -1.0, v13, s[76:77]
	v_cvt_i32_f32_e32 v21, v169
	v_min_i32_e32 v21, 0x3ff, v21
	v_lshl_add_u32 v21, v21, 2, s41
	v_cndmask_b32_e64 v21, v205, v21, s[76:77]
	ds_add_u32 v21, v206
	s_waitcnt lgkmcnt(7)
	v_sub_f32_e32 v14, v14, v192
	v_mul_f32_e32 v14, v14, v193
	v_cndmask_b32_e64 v170, -1.0, v14, s[78:79]
	v_cvt_i32_f32_e32 v22, v170
	v_min_i32_e32 v22, 0x3ff, v22
	v_lshl_add_u32 v22, v22, 2, s41
	v_cndmask_b32_e64 v22, v205, v22, s[78:79]
	ds_add_u32 v22, v206
	s_waitcnt lgkmcnt(7)
	v_sub_f32_e32 v15, v15, v192
	v_mul_f32_e32 v15, v15, v193
	v_cndmask_b32_e64 v171, -1.0, v15, s[80:81]
	v_cvt_i32_f32_e32 v23, v171
	v_min_i32_e32 v23, 0x3ff, v23
	v_lshl_add_u32 v23, v23, 2, s41
	v_cndmask_b32_e64 v23, v205, v23, s[80:81]
	ds_add_u32 v23, v206
	s_branch .Lsel_B_done
.Lsel_B_7_part:
	s_sub_i32 s2, s40, 0x1c00
	ds_read_b32 v8, v181 offset:28672
	ds_read_b32 v9, v181 offset:29184
	ds_read_b32 v10, v181 offset:29696
	ds_read_b32 v11, v181 offset:30208
	ds_read_b32 v12, v181 offset:30720
	ds_read_b32 v13, v181 offset:31232
	ds_read_b32 v14, v181 offset:31744
	ds_read_b32 v15, v181 offset:32256
	v_cmp_gt_i32_e64 s[66:67], s2, v180
	s_sub_i32 s3, s2, 0x80
	v_cmp_gt_i32_e64 s[68:69], s3, v180
	s_sub_i32 s3, s2, 0x100
	v_cmp_gt_i32_e64 s[70:71], s3, v180
	s_sub_i32 s3, s2, 0x180
	v_cmp_gt_i32_e64 s[72:73], s3, v180
	s_sub_i32 s3, s2, 0x200
	v_cmp_gt_i32_e64 s[74:75], s3, v180
	s_sub_i32 s3, s2, 0x280
	v_cmp_gt_i32_e64 s[76:77], s3, v180
	s_sub_i32 s3, s2, 0x300
	v_cmp_gt_i32_e64 s[78:79], s3, v180
	s_sub_i32 s3, s2, 0x380
	v_cmp_gt_i32_e64 s[80:81], s3, v180
	s_waitcnt lgkmcnt(7)
	v_sub_f32_e32 v8, v8, v192
	v_mul_f32_e32 v8, v8, v193
	v_cndmask_b32_e64 v172, -1.0, v8, s[66:67]
	v_cvt_i32_f32_e32 v16, v172
	v_min_i32_e32 v16, 0x3ff, v16
	v_lshl_add_u32 v16, v16, 2, s41
	v_cndmask_b32_e64 v16, v205, v16, s[66:67]
	ds_add_u32 v16, v206
	s_waitcnt lgkmcnt(7)
	v_sub_f32_e32 v9, v9, v192
	v_mul_f32_e32 v9, v9, v193
	v_cndmask_b32_e64 v173, -1.0, v9, s[68:69]
	v_cvt_i32_f32_e32 v17, v173
	v_min_i32_e32 v17, 0x3ff, v17
	v_lshl_add_u32 v17, v17, 2, s41
	v_cndmask_b32_e64 v17, v205, v17, s[68:69]
	ds_add_u32 v17, v206
	s_waitcnt lgkmcnt(7)
	v_sub_f32_e32 v10, v10, v192
	v_mul_f32_e32 v10, v10, v193
	v_cndmask_b32_e64 v174, -1.0, v10, s[70:71]
	v_cvt_i32_f32_e32 v18, v174
	v_min_i32_e32 v18, 0x3ff, v18
	v_lshl_add_u32 v18, v18, 2, s41
	v_cndmask_b32_e64 v18, v205, v18, s[70:71]
	ds_add_u32 v18, v206
	s_waitcnt lgkmcnt(7)
	v_sub_f32_e32 v11, v11, v192
	v_mul_f32_e32 v11, v11, v193
	v_cndmask_b32_e64 v175, -1.0, v11, s[72:73]
	v_cvt_i32_f32_e32 v19, v175
	v_min_i32_e32 v19, 0x3ff, v19
	v_lshl_add_u32 v19, v19, 2, s41
	v_cndmask_b32_e64 v19, v205, v19, s[72:73]
	ds_add_u32 v19, v206
	s_waitcnt lgkmcnt(7)
	v_sub_f32_e32 v12, v12, v192
	v_mul_f32_e32 v12, v12, v193
	v_cndmask_b32_e64 v176, -1.0, v12, s[74:75]
	v_cvt_i32_f32_e32 v20, v176
	v_min_i32_e32 v20, 0x3ff, v20
	v_lshl_add_u32 v20, v20, 2, s41
	v_cndmask_b32_e64 v20, v205, v20, s[74:75]
	ds_add_u32 v20, v206
	s_waitcnt lgkmcnt(7)
	v_sub_f32_e32 v13, v13, v192
	v_mul_f32_e32 v13, v13, v193
	v_cndmask_b32_e64 v177, -1.0, v13, s[76:77]
	v_cvt_i32_f32_e32 v21, v177
	v_min_i32_e32 v21, 0x3ff, v21
	v_lshl_add_u32 v21, v21, 2, s41
	v_cndmask_b32_e64 v21, v205, v21, s[76:77]
	ds_add_u32 v21, v206
	s_waitcnt lgkmcnt(7)
	v_sub_f32_e32 v14, v14, v192
	v_mul_f32_e32 v14, v14, v193
	v_cndmask_b32_e64 v178, -1.0, v14, s[78:79]
	v_cvt_i32_f32_e32 v22, v178
	v_min_i32_e32 v22, 0x3ff, v22
	v_lshl_add_u32 v22, v22, 2, s41
	v_cndmask_b32_e64 v22, v205, v22, s[78:79]
	ds_add_u32 v22, v206
	s_waitcnt lgkmcnt(7)
	v_sub_f32_e32 v15, v15, v192
	v_mul_f32_e32 v15, v15, v193
	v_cndmask_b32_e64 v179, -1.0, v15, s[80:81]
	v_cvt_i32_f32_e32 v23, v179
	v_min_i32_e32 v23, 0x3ff, v23
	v_lshl_add_u32 v23, v23, 2, s41
	v_cndmask_b32_e64 v23, v205, v23, s[80:81]
	ds_add_u32 v23, v206
; DI void lds_barrier() { asm volatile("s_waitcnt lgkmcnt(0)" ::: "memory"); __builtin_amdgcn_s_barrier(); asm volatile("" ::: "memory"); }
; DI void selectA_item(const Params& p, int item, int next_item, char* lds, bf16x8 (&qf)[4], float (&wq)[16]) {
;     ...
;     typedef int i32x4 __attribute__((ext_vector_type(4)));
;     const i32x4 h0 = *(const i32x4*)(histq + gt * 8), h1 = *(const i32x4*)(histq + gt * 8 + 4);
;     const int hh[8] = {h0.x, h0.y, h0.z, h0.w, h1.x, h1.y, h1.z, h1.w};
;     int tot = 0;
; #pragma unroll
;     for (int k = 0; k < 8; ++k) tot += hh[k];
;     int inc = tot;
; #pragma unroll
;     for (int o = 1; o < 64; o <<= 1) { const int ux = __shfl_down(inc, o); if (lane + o < 64) inc += ux; }
;     if (lane == 0) misc[wid] = inc;
;     lds_barrier();
;     {
;       int above = inc - tot + (upper ? 0 : misc[wid + 1]);
;       if (big) {
; #pragma unroll
;         for (int k = 7; k >= 0; --k) { const int c = hh[k]; if (above < 256 && above + c >= 256) { mq[1] = gt * 8 + k; mq[2] = 256 - above; mq[3] = c; } above += c; }
;       }
;     }
;     lds_barrier();
;     const int bstar = mq[1], need = mq[2], cnt = mq[3];
;     const float flo = (float)bstar, fhi = (bstar >= 1023) ? INFINITY : (float)(bstar + 1);
;     const bool tie = big && cnt != need;
.Lsel_B_done:
	s_waitcnt lgkmcnt(0)
	s_barrier
	s_cmp_lg_u32 s65, 0
	s_cbranch_scc1 .Lsel_D_skip
	v_sub_u32_e32 v0, 63, v183
	v_lshl_add_u32 v0, v0, 6, s41
	ds_read_b128 v[8:11], v0
	ds_read_b128 v[12:15], v0 offset:16
	ds_read_b128 v[16:19], v0 offset:32
	ds_read_b128 v[20:23], v0 offset:48
	s_waitcnt lgkmcnt(0)
	v_add3_u32 v24, v8, v9, v10
	v_add3_u32 v24, v24, v11, v12
	v_add3_u32 v24, v24, v13, v14
	v_add3_u32 v24, v24, v15, v16
	v_add3_u32 v24, v24, v17, v18
	v_add3_u32 v24, v24, v19, v20
	v_add3_u32 v24, v24, v21, v22
	v_add_u32_e32 v24, v24, v23
	v_mov_b32_e32 v25, v24
	s_nop 1
	v_add_u32_dpp v25, v25, v25 row_shr:1 row_mask:0xf bank_mask:0xf
	s_nop 1
	v_add_u32_dpp v25, v25, v25 row_shr:2 row_mask:0xf bank_mask:0xf
	s_nop 1
	v_add_u32_dpp v25, v25, v25 row_shr:4 row_mask:0xf bank_mask:0xf
	s_nop 1
	v_add_u32_dpp v25, v25, v25 row_shr:8 row_mask:0xf bank_mask:0xf
	s_nop 1
	v_add_u32_dpp v25, v25, v25 row_bcast:15 row_mask:0xa bank_mask:0xf
	s_nop 1
	v_add_u32_dpp v25, v25, v25 row_bcast:31 row_mask:0xc bank_mask:0xf
	s_nop 1
	v_sub_u32_e32 v26, v25, v24
	v_sub_u32_e32 v27, 0x100, v26
	v_mov_b32_e32 v30, -1
	v_mov_b32_e32 v31, 0
	v_mov_b32_e32 v50, 0
	v_add_u32_e32 v29, -1, v27
	v_cmp_lt_u32_e64 s[46:47], v29, v23
	v_sub_u32_e32 v28, v27, v23
	s_nop 0
	v_cndmask_b32_e64 v30, v30, 15, s[46:47]
	v_cndmask_b32_e64 v31, v31, v27, s[46:47]
	v_cndmask_b32_e64 v50, v50, v23, s[46:47]
	v_add_u32_e32 v29, -1, v28
	v_cmp_lt_u32_e64 s[48:49], v29, v22
	v_sub_u32_e32 v27, v28, v22
	s_nop 0
	v_cndmask_b32_e64 v30, v30, 14, s[48:49]
	v_cndmask_b32_e64 v31, v31, v28, s[48:49]
	v_cndmask_b32_e64 v50, v50, v22, s[48:49]
	v_add_u32_e32 v29, -1, v27
	v_cmp_lt_u32_e64 s[46:47], v29, v21
	v_sub_u32_e32 v28, v27, v21
	s_nop 0
	v_cndmask_b32_e64 v30, v30, 13, s[46:47]
	v_cndmask_b32_e64 v31, v31, v27, s[46:47]
	v_cndmask_b32_e64 v50, v50, v21, s[46:47]
	v_add_u32_e32 v29, -1, v28
	v_cmp_lt_u32_e64 s[48:49], v29, v20
	v_sub_u32_e32 v27, v28, v20
	s_nop 0
	v_cndmask_b32_e64 v30, v30, 12, s[48:49]
	v_cndmask_b32_e64 v31, v31, v28, s[48:49]
	v_cndmask_b32_e64 v50, v50, v20, s[48:49]
	v_add_u32_e32 v29, -1, v27
	v_cmp_lt_u32_e64 s[46:47], v29, v19
	v_sub_u32_e32 v28, v27, v19
	s_nop 0
	v_cndmask_b32_e64 v30, v30, 11, s[46:47]
	v_cndmask_b32_e64 v31, v31, v27, s[46:47]
	v_cndmask_b32_e64 v50, v50, v19, s[46:47]
	v_add_u32_e32 v29, -1, v28
	v_cmp_lt_u32_e64 s[48:49], v29, v18
	v_sub_u32_e32 v27, v28, v18
	s_nop 0
	v_cndmask_b32_e64 v30, v30, 10, s[48:49]
	v_cndmask_b32_e64 v31, v31, v28, s[48:49]
	v_cndmask_b32_e64 v50, v50, v18, s[48:49]
	v_add_u32_e32 v29, -1, v27
	v_cmp_lt_u32_e64 s[46:47], v29, v17
	v_sub_u32_e32 v28, v27, v17
	s_nop 0
	v_cndmask_b32_e64 v30, v30, 9, s[46:47]
	v_cndmask_b32_e64 v31, v31, v27, s[46:47]
	v_cndmask_b32_e64 v50, v50, v17, s[46:47]
	v_add_u32_e32 v29, -1, v28
	v_cmp_lt_u32_e64 s[48:49], v29, v16
	v_sub_u32_e32 v27, v28, v16
	s_nop 0
	v_cndmask_b32_e64 v30, v30, 8, s[48:49]
	v_cndmask_b32_e64 v31, v31, v28, s[48:49]
	v_cndmask_b32_e64 v50, v50, v16, s[48:49]
	v_add_u32_e32 v29, -1, v27
	v_cmp_lt_u32_e64 s[46:47], v29, v15
	v_sub_u32_e32 v28, v27, v15
	s_nop 0
	v_cndmask_b32_e64 v30, v30, 7, s[46:47]
	v_cndmask_b32_e64 v31, v31, v27, s[46:47]
	v_cndmask_b32_e64 v50, v50, v15, s[46:47]
	v_add_u32_e32 v29, -1, v28
	v_cmp_lt_u32_e64 s[48:49], v29, v14
	v_sub_u32_e32 v27, v28, v14
	s_nop 0
	v_cndmask_b32_e64 v30, v30, 6, s[48:49]
	v_cndmask_b32_e64 v31, v31, v28, s[48:49]
	v_cndmask_b32_e64 v50, v50, v14, s[48:49]
	v_add_u32_e32 v29, -1, v27
	v_cmp_lt_u32_e64 s[46:47], v29, v13
	v_sub_u32_e32 v28, v27, v13
	s_nop 0
	v_cndmask_b32_e64 v30, v30, 5, s[46:47]
	v_cndmask_b32_e64 v31, v31, v27, s[46:47]
	v_cndmask_b32_e64 v50, v50, v13, s[46:47]
	v_add_u32_e32 v29, -1, v28
	v_cmp_lt_u32_e64 s[48:49], v29, v12
	v_sub_u32_e32 v27, v28, v12
	s_nop 0
	v_cndmask_b32_e64 v30, v30, 4, s[48:49]
	v_cndmask_b32_e64 v31, v31, v28, s[48:49]
	v_cndmask_b32_e64 v50, v50, v12, s[48:49]
	v_add_u32_e32 v29, -1, v27
	v_cmp_lt_u32_e64 s[46:47], v29, v11
	v_sub_u32_e32 v28, v27, v11
	s_nop 0
	v_cndmask_b32_e64 v30, v30, 3, s[46:47]
	v_cndmask_b32_e64 v31, v31, v27, s[46:47]
	v_cndmask_b32_e64 v50, v50, v11, s[46:47]
	v_add_u32_e32 v29, -1, v28
	v_cmp_lt_u32_e64 s[48:49], v29, v10
	v_sub_u32_e32 v27, v28, v10
	s_nop 0
	v_cndmask_b32_e64 v30, v30, 2, s[48:49]
	v_cndmask_b32_e64 v31, v31, v28, s[48:49]
	v_cndmask_b32_e64 v50, v50, v10, s[48:49]
	v_add_u32_e32 v29, -1, v27
	v_cmp_lt_u32_e64 s[46:47], v29, v9
	v_sub_u32_e32 v28, v27, v9
	s_nop 0
	v_cndmask_b32_e64 v30, v30, 1, s[46:47]
	v_cndmask_b32_e64 v31, v31, v27, s[46:47]
	v_cndmask_b32_e64 v50, v50, v9, s[46:47]
	v_add_u32_e32 v29, -1, v28
	v_cmp_lt_u32_e64 s[48:49], v29, v8
	v_sub_u32_e32 v27, v28, v8
	s_nop 0
	v_cndmask_b32_e64 v30, v30, 0, s[48:49]
	v_cndmask_b32_e64 v31, v31, v28, s[48:49]
	v_cndmask_b32_e64 v50, v50, v8, s[48:49]
	v_cmp_le_i32_e32 vcc, 0, v30
	s_nop 3
	s_cmp_eq_u64 vcc, 0
	s_cbranch_scc1 .Lsel_fallback
	s_ff1_i32_b64 s64, vcc
	s_nop 0
	v_readlane_b32 s58, v30, s64
	v_readlane_b32 s59, v31, s64
	v_readlane_b32 s60, v50, s64
	s_sub_i32 s2, 63, s64
	s_lshl_b32 s2, s2, 4
	s_add_i32 s58, s58, s2
	s_cmp_gt_u32 s60, 0x80
	s_cbranch_scc1 .Lsel_fallback
	s_sub_i32 s61, 0x100, s59
	v_cvt_f32_i32_e32 v194, s58
	s_add_i32 s2, s58, 1
	v_cvt_f32_i32_e32 v195, s2
	s_cmp_ge_u32 s58, 0x3ff
	s_cbranch_scc0 .Lsel_fhi_ok
	v_mov_b32_e32 v195, 0x7f800000
; DI unsigned long long mkcmp(float v, int idx) { return ((unsigned long long)f2ord(v) << 16) | ((unsigned long long)(8191 - idx) << 3); }
; DI void selectA_item(const Params& p, int item, int next_item, char* lds, bf16x8 (&qf)[4], float (&wq)[16]) {
;     ...
;     unsigned long long selm = 0ull;
;     if (fast) {
; #pragma unroll
;       for (int i = 0; i < 64; ++i) { const int idx = gt + 128 * i;
;         if (idx < n) { const float u = uu[i]; bool sel = u >= fhi; if (!sel && u >= flo) sel = !tie || (mkcmp(scq[idx], idx) >= T); if (sel) selm |= (1ull << i); } }
;     }
.Lsel_fhi_ok:
	v_mov_b32_e32 v196, 0
	v_mov_b32_e32 v197, 0
	v_mov_b32_e32 v198, 0
	v_mov_b32_e32 v199, 0
	v_cmp_ge_f32_e64 s[46:47], v116, v195
	v_cmp_ge_f32_e64 s[50:51], v116, v194
	v_cmp_ge_f32_e64 s[48:49], v117, v195
	v_cmp_ge_f32_e64 s[54:55], v117, v194
	v_addc_co_u32_e64 v196, s[56:57], v196, v196, s[46:47]
	v_addc_co_u32_e64 v198, s[56:57], v198, v198, s[50:51]
	v_cmp_ge_f32_e64 s[46:47], v118, v195
	v_cmp_ge_f32_e64 s[50:51], v118, v194
	v_addc_co_u32_e64 v196, s[56:57], v196, v196, s[48:49]
	v_addc_co_u32_e64 v198, s[56:57], v198, v198, s[54:55]
	v_cmp_ge_f32_e64 s[48:49], v119, v195
	v_cmp_ge_f32_e64 s[54:55], v119, v194
	v_addc_co_u32_e64 v196, s[56:57], v196, v196, s[46:47]
	v_addc_co_u32_e64 v198, s[56:57], v198, v198, s[50:51]
	v_cmp_ge_f32_e64 s[46:47], v120, v195
	v_cmp_ge_f32_e64 s[50:51], v120, v194
	v_addc_co_u32_e64 v196, s[56:57], v196, v196, s[48:49]
	v_addc_co_u32_e64 v198, s[56:57], v198, v198, s[54:55]
	v_cmp_ge_f32_e64 s[48:49], v121, v195
	v_cmp_ge_f32_e64 s[54:55], v121, v194
	v_addc_co_u32_e64 v196, s[56:57], v196, v196, s[46:47]
	v_addc_co_u32_e64 v198, s[56:57], v198, v198, s[50:51]
	v_cmp_ge_f32_e64 s[46:47], v122, v195
	v_cmp_ge_f32_e64 s[50:51], v122, v194
	v_addc_co_u32_e64 v196, s[56:57], v196, v196, s[48:49]
	v_addc_co_u32_e64 v198, s[56:57], v198, v198, s[54:55]
	v_cmp_ge_f32_e64 s[48:49], v123, v195
	v_cmp_ge_f32_e64 s[54:55], v123, v194
	v_addc_co_u32_e64 v196, s[56:57], v196, v196, s[46:47]
	v_addc_co_u32_e64 v198, s[56:57], v198, v198, s[50:51]
	v_addc_co_u32_e64 v196, s[56:57], v196, v196, s[48:49]
	v_addc_co_u32_e64 v198, s[56:57], v198, v198, s[54:55]
	s_cmp_le_u32 s40, 0x400
	s_cbranch_scc1 .Lsel_D_masks_done
	v_cmp_ge_f32_e64 s[46:47], v124, v195
	v_cmp_ge_f32_e64 s[50:51], v124, v194
	v_cmp_ge_f32_e64 s[48:49], v125, v195
	v_cmp_ge_f32_e64 s[54:55], v125, v194
	v_addc_co_u32_e64 v196, s[56:57], v196, v196, s[46:47]
	v_addc_co_u32_e64 v198, s[56:57], v198, v198, s[50:51]
	v_cmp_ge_f32_e64 s[46:47], v126, v195
	v_cmp_ge_f32_e64 s[50:51], v126, v194
	v_addc_co_u32_e64 v196, s[56:57], v196, v196, s[48:49]
	v_addc_co_u32_e64 v198, s[56:57], v198, v198, s[54:55]
	v_cmp_ge_f32_e64 s[48:49], v127, v195
	v_cmp_ge_f32_e64 s[54:55], v127, v194
	v_addc_co_u32_e64 v196, s[56:57], v196, v196, s[46:47]
	v_addc_co_u32_e64 v198, s[56:57], v198, v198, s[50:51]
	v_cmp_ge_f32_e64 s[46:47], v128, v195
	v_cmp_ge_f32_e64 s[50:51], v128, v194
	v_addc_co_u32_e64 v196, s[56:57], v196, v196, s[48:49]
	v_addc_co_u32_e64 v198, s[56:57], v198, v198, s[54:55]
	v_cmp_ge_f32_e64 s[48:49], v129, v195
	v_cmp_ge_f32_e64 s[54:55], v129, v194
	v_addc_co_u32_e64 v196, s[56:57], v196, v196, s[46:47]
	v_addc_co_u32_e64 v198, s[56:57], v198, v198, s[50:51]
	v_cmp_ge_f32_e64 s[46:47], v130, v195
	v_cmp_ge_f32_e64 s[50:51], v130, v194
	v_addc_co_u32_e64 v196, s[56:57], v196, v196, s[48:49]
	v_addc_co_u32_e64 v198, s[56:57], v198, v198, s[54:55]
	v_cmp_ge_f32_e64 s[48:49], v131, v195
	v_cmp_ge_f32_e64 s[54:55], v131, v194
	v_addc_co_u32_e64 v196, s[56:57], v196, v196, s[46:47]
	v_addc_co_u32_e64 v198, s[56:57], v198, v198, s[50:51]
	v_addc_co_u32_e64 v196, s[56:57], v196, v196, s[48:49]
	v_addc_co_u32_e64 v198, s[56:57], v198, v198, s[54:55]
	s_cmp_le_u32 s40, 0x800
	s_cbranch_scc1 .Lsel_D_masks_done
	v_cmp_ge_f32_e64 s[46:47], v132, v195
	v_cmp_ge_f32_e64 s[50:51], v132, v194
	v_cmp_ge_f32_e64 s[48:49], v133, v195
	v_cmp_ge_f32_e64 s[54:55], v133, v194
	v_addc_co_u32_e64 v196, s[56:57], v196, v196, s[46:47]
	v_addc_co_u32_e64 v198, s[56:57], v198, v198, s[50:51]
	v_cmp_ge_f32_e64 s[46:47], v134, v195
	v_cmp_ge_f32_e64 s[50:51], v134, v194
	v_addc_co_u32_e64 v196, s[56:57], v196, v196, s[48:49]
	v_addc_co_u32_e64 v198, s[56:57], v198, v198, s[54:55]
	v_cmp_ge_f32_e64 s[48:49], v135, v195
	v_cmp_ge_f32_e64 s[54:55], v135, v194
	v_addc_co_u32_e64 v196, s[56:57], v196, v196, s[46:47]
	v_addc_co_u32_e64 v198, s[56:57], v198, v198, s[50:51]
	v_cmp_ge_f32_e64 s[46:47], v136, v195
	v_cmp_ge_f32_e64 s[50:51], v136, v194
	v_addc_co_u32_e64 v196, s[56:57], v196, v196, s[48:49]
	v_addc_co_u32_e64 v198, s[56:57], v198, v198, s[54:55]
	v_cmp_ge_f32_e64 s[48:49], v137, v195
	v_cmp_ge_f32_e64 s[54:55], v137, v194
	v_addc_co_u32_e64 v196, s[56:57], v196, v196, s[46:47]
	v_addc_co_u32_e64 v198, s[56:57], v198, v198, s[50:51]
	v_cmp_ge_f32_e64 s[46:47], v138, v195
	v_cmp_ge_f32_e64 s[50:51], v138, v194
	v_addc_co_u32_e64 v196, s[56:57], v196, v196, s[48:49]
	v_addc_co_u32_e64 v198, s[56:57], v198, v198, s[54:55]
	v_cmp_ge_f32_e64 s[48:49], v139, v195
	v_cmp_ge_f32_e64 s[54:55], v139, v194
	v_addc_co_u32_e64 v196, s[56:57], v196, v196, s[46:47]
	v_addc_co_u32_e64 v198, s[56:57], v198, v198, s[50:51]
	v_addc_co_u32_e64 v196, s[56:57], v196, v196, s[48:49]
	v_addc_co_u32_e64 v198, s[56:57], v198, v198, s[54:55]
	s_cmp_le_u32 s40, 0xc00
	s_cbranch_scc1 .Lsel_D_masks_done
	v_cmp_ge_f32_e64 s[46:47], v140, v195
	v_cmp_ge_f32_e64 s[50:51], v140, v194
	v_cmp_ge_f32_e64 s[48:49], v141, v195
	v_cmp_ge_f32_e64 s[54:55], v141, v194
	v_addc_co_u32_e64 v196, s[56:57], v196, v196, s[46:47]
	v_addc_co_u32_e64 v198, s[56:57], v198, v198, s[50:51]
	v_cmp_ge_f32_e64 s[46:47], v142, v195
	v_cmp_ge_f32_e64 s[50:51], v142, v194
	v_addc_co_u32_e64 v196, s[56:57], v196, v196, s[48:49]
	v_addc_co_u32_e64 v198, s[56:57], v198, v198, s[54:55]
	v_cmp_ge_f32_e64 s[48:49], v143, v195
	v_cmp_ge_f32_e64 s[54:55], v143, v194
	v_addc_co_u32_e64 v196, s[56:57], v196, v196, s[46:47]
	v_addc_co_u32_e64 v198, s[56:57], v198, v198, s[50:51]
	v_cmp_ge_f32_e64 s[46:47], v144, v195
	v_cmp_ge_f32_e64 s[50:51], v144, v194
	v_addc_co_u32_e64 v196, s[56:57], v196, v196, s[48:49]
	v_addc_co_u32_e64 v198, s[56:57], v198, v198, s[54:55]
	v_cmp_ge_f32_e64 s[48:49], v145, v195
	v_cmp_ge_f32_e64 s[54:55], v145, v194
	v_addc_co_u32_e64 v196, s[56:57], v196, v196, s[46:47]
	v_addc_co_u32_e64 v198, s[56:57], v198, v198, s[50:51]
	v_cmp_ge_f32_e64 s[46:47], v146, v195
	v_cmp_ge_f32_e64 s[50:51], v146, v194
	v_addc_co_u32_e64 v196, s[56:57], v196, v196, s[48:49]
	v_addc_co_u32_e64 v198, s[56:57], v198, v198, s[54:55]
	v_cmp_ge_f32_e64 s[48:49], v147, v195
	v_cmp_ge_f32_e64 s[54:55], v147, v194
	v_addc_co_u32_e64 v196, s[56:57], v196, v196, s[46:47]
	v_addc_co_u32_e64 v198, s[56:57], v198, v198, s[50:51]
	v_addc_co_u32_e64 v196, s[56:57], v196, v196, s[48:49]
	v_addc_co_u32_e64 v198, s[56:57], v198, v198, s[54:55]
	s_cmp_le_u32 s40, 0x1000
	s_cbranch_scc1 .Lsel_D_masks_done
; DI unsigned long long mkcmp(float v, int idx) { return ((unsigned long long)f2ord(v) << 16) | ((unsigned long long)(8191 - idx) << 3); }
; DI void selectA_item(const Params& p, int item, int next_item, char* lds, bf16x8 (&qf)[4], float (&wq)[16]) {
;     ...
;     unsigned long long selm = 0ull;
;     if (fast) {
; #pragma unroll
;       for (int i = 0; i < 64; ++i) { const int idx = gt + 128 * i;
;         if (idx < n) { const float u = uu[i]; bool sel = u >= fhi; if (!sel && u >= flo) sel = !tie || (mkcmp(scq[idx], idx) >= T); if (sel) selm |= (1ull << i); } }
;     }
	v_cmp_ge_f32_e64 s[46:47], v148, v195
	v_cmp_ge_f32_e64 s[50:51], v148, v194
	v_cmp_ge_f32_e64 s[48:49], v149, v195
	v_cmp_ge_f32_e64 s[54:55], v149, v194
	v_addc_co_u32_e64 v197, s[56:57], v197, v197, s[46:47]
	v_addc_co_u32_e64 v199, s[56:57], v199, v199, s[50:51]
	v_cmp_ge_f32_e64 s[46:47], v150, v195
	v_cmp_ge_f32_e64 s[50:51], v150, v194
	v_addc_co_u32_e64 v197, s[56:57], v197, v197, s[48:49]
	v_addc_co_u32_e64 v199, s[56:57], v199, v199, s[54:55]
	v_cmp_ge_f32_e64 s[48:49], v151, v195
	v_cmp_ge_f32_e64 s[54:55], v151, v194
	v_addc_co_u32_e64 v197, s[56:57], v197, v197, s[46:47]
	v_addc_co_u32_e64 v199, s[56:57], v199, v199, s[50:51]
	v_cmp_ge_f32_e64 s[46:47], v152, v195
	v_cmp_ge_f32_e64 s[50:51], v152, v194
	v_addc_co_u32_e64 v197, s[56:57], v197, v197, s[48:49]
	v_addc_co_u32_e64 v199, s[56:57], v199, v199, s[54:55]
	v_cmp_ge_f32_e64 s[48:49], v153, v195
	v_cmp_ge_f32_e64 s[54:55], v153, v194
	v_addc_co_u32_e64 v197, s[56:57], v197, v197, s[46:47]
	v_addc_co_u32_e64 v199, s[56:57], v199, v199, s[50:51]
	v_cmp_ge_f32_e64 s[46:47], v154, v195
	v_cmp_ge_f32_e64 s[50:51], v154, v194
	v_addc_co_u32_e64 v197, s[56:57], v197, v197, s[48:49]
	v_addc_co_u32_e64 v199, s[56:57], v199, v199, s[54:55]
	v_cmp_ge_f32_e64 s[48:49], v155, v195
	v_cmp_ge_f32_e64 s[54:55], v155, v194
	v_addc_co_u32_e64 v197, s[56:57], v197, v197, s[46:47]
	v_addc_co_u32_e64 v199, s[56:57], v199, v199, s[50:51]
	v_addc_co_u32_e64 v197, s[56:57], v197, v197, s[48:49]
	v_addc_co_u32_e64 v199, s[56:57], v199, v199, s[54:55]
	s_cmp_le_u32 s40, 0x1400
	s_cbranch_scc1 .Lsel_D_masks_done
	v_cmp_ge_f32_e64 s[46:47], v156, v195
	v_cmp_ge_f32_e64 s[50:51], v156, v194
	v_cmp_ge_f32_e64 s[48:49], v157, v195
	v_cmp_ge_f32_e64 s[54:55], v157, v194
	v_addc_co_u32_e64 v197, s[56:57], v197, v197, s[46:47]
	v_addc_co_u32_e64 v199, s[56:57], v199, v199, s[50:51]
	v_cmp_ge_f32_e64 s[46:47], v158, v195
	v_cmp_ge_f32_e64 s[50:51], v158, v194
	v_addc_co_u32_e64 v197, s[56:57], v197, v197, s[48:49]
	v_addc_co_u32_e64 v199, s[56:57], v199, v199, s[54:55]
	v_cmp_ge_f32_e64 s[48:49], v159, v195
	v_cmp_ge_f32_e64 s[54:55], v159, v194
	v_addc_co_u32_e64 v197, s[56:57], v197, v197, s[46:47]
	v_addc_co_u32_e64 v199, s[56:57], v199, v199, s[50:51]
	v_cmp_ge_f32_e64 s[46:47], v160, v195
	v_cmp_ge_f32_e64 s[50:51], v160, v194
	v_addc_co_u32_e64 v197, s[56:57], v197, v197, s[48:49]
	v_addc_co_u32_e64 v199, s[56:57], v199, v199, s[54:55]
	v_cmp_ge_f32_e64 s[48:49], v161, v195
	v_cmp_ge_f32_e64 s[54:55], v161, v194
	v_addc_co_u32_e64 v197, s[56:57], v197, v197, s[46:47]
	v_addc_co_u32_e64 v199, s[56:57], v199, v199, s[50:51]
	v_cmp_ge_f32_e64 s[46:47], v162, v195
	v_cmp_ge_f32_e64 s[50:51], v162, v194
	v_addc_co_u32_e64 v197, s[56:57], v197, v197, s[48:49]
	v_addc_co_u32_e64 v199, s[56:57], v199, v199, s[54:55]
	v_cmp_ge_f32_e64 s[48:49], v163, v195
	v_cmp_ge_f32_e64 s[54:55], v163, v194
	v_addc_co_u32_e64 v197, s[56:57], v197, v197, s[46:47]
	v_addc_co_u32_e64 v199, s[56:57], v199, v199, s[50:51]
	v_addc_co_u32_e64 v197, s[56:57], v197, v197, s[48:49]
	v_addc_co_u32_e64 v199, s[56:57], v199, v199, s[54:55]
	s_cmp_le_u32 s40, 0x1800
	s_cbranch_scc1 .Lsel_D_masks_done
	v_cmp_ge_f32_e64 s[46:47], v164, v195
	v_cmp_ge_f32_e64 s[50:51], v164, v194
	v_cmp_ge_f32_e64 s[48:49], v165, v195
	v_cmp_ge_f32_e64 s[54:55], v165, v194
	v_addc_co_u32_e64 v197, s[56:57], v197, v197, s[46:47]
	v_addc_co_u32_e64 v199, s[56:57], v199, v199, s[50:51]
	v_cmp_ge_f32_e64 s[46:47], v166, v195
	v_cmp_ge_f32_e64 s[50:51], v166, v194
	v_addc_co_u32_e64 v197, s[56:57], v197, v197, s[48:49]
	v_addc_co_u32_e64 v199, s[56:57], v199, v199, s[54:55]
	v_cmp_ge_f32_e64 s[48:49], v167, v195
	v_cmp_ge_f32_e64 s[54:55], v167, v194
	v_addc_co_u32_e64 v197, s[56:57], v197, v197, s[46:47]
	v_addc_co_u32_e64 v199, s[56:57], v199, v199, s[50:51]
	v_cmp_ge_f32_e64 s[46:47], v168, v195
	v_cmp_ge_f32_e64 s[50:51], v168, v194
	v_addc_co_u32_e64 v197, s[56:57], v197, v197, s[48:49]
	v_addc_co_u32_e64 v199, s[56:57], v199, v199, s[54:55]
	v_cmp_ge_f32_e64 s[48:49], v169, v195
	v_cmp_ge_f32_e64 s[54:55], v169, v194
	v_addc_co_u32_e64 v197, s[56:57], v197, v197, s[46:47]
	v_addc_co_u32_e64 v199, s[56:57], v199, v199, s[50:51]
	v_cmp_ge_f32_e64 s[46:47], v170, v195
	v_cmp_ge_f32_e64 s[50:51], v170, v194
	v_addc_co_u32_e64 v197, s[56:57], v197, v197, s[48:49]
	v_addc_co_u32_e64 v199, s[56:57], v199, v199, s[54:55]
	v_cmp_ge_f32_e64 s[48:49], v171, v195
	v_cmp_ge_f32_e64 s[54:55], v171, v194
	v_addc_co_u32_e64 v197, s[56:57], v197, v197, s[46:47]
	v_addc_co_u32_e64 v199, s[56:57], v199, v199, s[50:51]
	v_addc_co_u32_e64 v197, s[56:57], v197, v197, s[48:49]
	v_addc_co_u32_e64 v199, s[56:57], v199, v199, s[54:55]
	s_cmp_le_u32 s40, 0x1c00
	s_cbranch_scc1 .Lsel_D_masks_done
	v_cmp_ge_f32_e64 s[46:47], v172, v195
	v_cmp_ge_f32_e64 s[50:51], v172, v194
	v_cmp_ge_f32_e64 s[48:49], v173, v195
	v_cmp_ge_f32_e64 s[54:55], v173, v194
	v_addc_co_u32_e64 v197, s[56:57], v197, v197, s[46:47]
	v_addc_co_u32_e64 v199, s[56:57], v199, v199, s[50:51]
	v_cmp_ge_f32_e64 s[46:47], v174, v195
	v_cmp_ge_f32_e64 s[50:51], v174, v194
	v_addc_co_u32_e64 v197, s[56:57], v197, v197, s[48:49]
	v_addc_co_u32_e64 v199, s[56:57], v199, v199, s[54:55]
	v_cmp_ge_f32_e64 s[48:49], v175, v195
	v_cmp_ge_f32_e64 s[54:55], v175, v194
	v_addc_co_u32_e64 v197, s[56:57], v197, v197, s[46:47]
	v_addc_co_u32_e64 v199, s[56:57], v199, v199, s[50:51]
	v_cmp_ge_f32_e64 s[46:47], v176, v195
	v_cmp_ge_f32_e64 s[50:51], v176, v194
	v_addc_co_u32_e64 v197, s[56:57], v197, v197, s[48:49]
	v_addc_co_u32_e64 v199, s[56:57], v199, v199, s[54:55]
	v_cmp_ge_f32_e64 s[48:49], v177, v195
	v_cmp_ge_f32_e64 s[54:55], v177, v194
	v_addc_co_u32_e64 v197, s[56:57], v197, v197, s[46:47]
	v_addc_co_u32_e64 v199, s[56:57], v199, v199, s[50:51]
	v_cmp_ge_f32_e64 s[46:47], v178, v195
	v_cmp_ge_f32_e64 s[50:51], v178, v194
	v_addc_co_u32_e64 v197, s[56:57], v197, v197, s[48:49]
	v_addc_co_u32_e64 v199, s[56:57], v199, v199, s[54:55]
	v_cmp_ge_f32_e64 s[48:49], v179, v195
	v_cmp_ge_f32_e64 s[54:55], v179, v194
	v_addc_co_u32_e64 v197, s[56:57], v197, v197, s[46:47]
	v_addc_co_u32_e64 v199, s[56:57], v199, v199, s[50:51]
	v_addc_co_u32_e64 v197, s[56:57], v197, v197, s[48:49]
	v_addc_co_u32_e64 v199, s[56:57], v199, v199, s[54:55]
; DI void lds_barrier() { asm volatile("s_waitcnt lgkmcnt(0)" ::: "memory"); __builtin_amdgcn_s_barrier(); asm volatile("" ::: "memory"); }
; DI unsigned long long mkcmp(float v, int idx) { return ((unsigned long long)f2ord(v) << 16) | ((unsigned long long)(8191 - idx) << 3); }
; DI void selectA_item(const Params& p, int item, int next_item, char* lds, bf16x8 (&qf)[4], float (&wq)[16]) {
;     ...
;     const bool tie = big && cnt != need;
;     if (tie) {
;       if (cnt <= 128) {
; #pragma unroll
;         for (int i = 0; i < 64; ++i) { const int idx = gt + 128 * i; if (idx < n && uu[i] >= flo && uu[i] < fhi) { const int slot = atomicAdd(&mq[0], 1); clq[slot] = mkcmp(scq[idx], idx); } }
;       } else if (gt == 0) mq[6] = 1;
;     }
;     lds_barrier();
;     if (tie && cnt <= 128 && gt < cnt) { const unsigned long long c = clq[gt]; int rank = 0; for (int jx = 0; jx < cnt; ++jx) rank += (clq[jx] > c) ? 1 : 0;
;       if (rank == need - 1) { mq[4] = (int)(unsigned)(c & 0xffffffffull); mq[5] = (int)(unsigned)(c >> 32); } }
;     lds_barrier();
;     const unsigned long long T = tie ? (((unsigned long long)(unsigned)mq[5] << 32) | (unsigned long long)(unsigned)mq[4]) : 0ull;
;     const bool fast = big && !(tie && cnt > 128);
;     unsigned long long selm = 0ull;
;     if (fast) {
; #pragma unroll
;       for (int i = 0; i < 64; ++i) { const int idx = gt + 128 * i;
;         if (idx < n) { const float u = uu[i]; bool sel = u >= fhi; if (!sel && u >= flo) sel = !tie || (mkcmp(scq[idx], idx) >= T); if (sel) selm |= (1ull << i); } }
;     }
;     const int mycnt = __popcll(selm);
;     int pinc = mycnt;
; #pragma unroll
;     for (int o = 1; o < 64; o <<= 1) { const int ux = __shfl_up(pinc, o); if (lane >= o) pinc += ux; }
;     if (lane == 63) misc[8 + wid] = pinc;
;     lds_barrier();
;     if (fast) {
;       int pos = pinc - mycnt + (upper ? misc[8 + wid - 1] : 0);
;       while (selm) { const int i = __ffsll((long long)selm) - 1; selm &= selm - 1ull; if (pos < 256) out[pos] = (unsigned short)(gt + 128 * i); ++pos; }
;     } else if (!big) {
;       for (int i = gt; i < n; i += 128) out[i] = (unsigned short)i;
.Lsel_D_masks_done:
	s_add_i32 s2, s40, 0x3ff
	s_lshr_b32 s2, s2, 10
	s_min_u32 s3, s2, 4
	s_lshl_b32 s3, s3, 3
	s_sub_i32 s44, 32, s3
	s_sub_i32 s4, s2, 4
	s_max_i32 s4, s4, 0
	s_lshl_b32 s4, s4, 3
	s_sub_i32 s45, 32, s4
	v_lshlrev_b32_e32 v196, s44, v196
	v_lshlrev_b32_e32 v198, s44, v198
	v_lshlrev_b32_e32 v197, s45, v197
	v_lshlrev_b32_e32 v199, s45, v199
	v_xor_b32_e32 v198, v198, v196
	v_xor_b32_e32 v199, v199, v197
	v_or_b32_e32 v0, v198, v199
	v_cmp_ne_u32_e32 vcc, 0, v0
	s_cbranch_vccz .Lsel_cand_done
	v_cmp_ne_u32_e32 vcc, 0, v198
	s_and_saveexec_b64 s[0:1], vcc
	s_cbranch_execz .Lsel_cand0_done
.Lsel_cand0_loop:
	v_ffbh_u32_e32 v1, v198
	v_lshrrev_b32_e32 v2, v1, v204
	v_xor_b32_e32 v198, v198, v2
	v_lshl_add_u32 v3, v1, 7, v180
	v_lshl_add_u32 v4, v3, 2, s84
	ds_read_b32 v5, v4
	ds_add_rtn_u32 v6, v207, v206
	v_sub_u32_e32 v8, 0x1fff, v3
	v_lshlrev_b32_e32 v8, 3, v8
	s_waitcnt lgkmcnt(0)
	v_add_f32_e32 v5, 0, v5
	v_ashrrev_i32_e32 v7, 31, v5
	v_or_b32_e32 v7, 0x80000000, v7
	v_xor_b32_e32 v5, v5, v7
	v_lshl_or_b32 v10, v5, 16, v8
	v_lshrrev_b32_e32 v11, 16, v5
	v_lshl_add_u32 v9, v6, 3, s43
	ds_write_b64 v9, v[10:11]
	v_cmp_ne_u32_e32 vcc, 0, v198
	s_and_b64 exec, exec, vcc
	s_cbranch_execnz .Lsel_cand0_loop
.Lsel_cand0_done:
	s_mov_b64 exec, s[0:1]
	v_cmp_ne_u32_e32 vcc, 0, v199
	s_and_saveexec_b64 s[0:1], vcc
	s_cbranch_execz .Lsel_cand1_done
.Lsel_cand1_loop:
	v_ffbh_u32_e32 v1, v199
	v_lshrrev_b32_e32 v2, v1, v204
	v_xor_b32_e32 v199, v199, v2
	v_lshl_add_u32 v3, v1, 7, v180
	v_add_u32_e32 v3, 0x1000, v3
	v_lshl_add_u32 v4, v3, 2, s84
	ds_read_b32 v5, v4
	ds_add_rtn_u32 v6, v207, v206
	v_sub_u32_e32 v8, 0x1fff, v3
	v_lshlrev_b32_e32 v8, 3, v8
	s_waitcnt lgkmcnt(0)
	v_add_f32_e32 v5, 0, v5
	v_ashrrev_i32_e32 v7, 31, v5
	v_or_b32_e32 v7, 0x80000000, v7
	v_xor_b32_e32 v5, v5, v7
	v_lshl_or_b32 v10, v5, 16, v8
	v_lshrrev_b32_e32 v11, 16, v5
	v_lshl_add_u32 v9, v6, 3, s43
	ds_write_b64 v9, v[10:11]
	v_cmp_ne_u32_e32 vcc, 0, v199
	s_and_b64 exec, exec, vcc
	s_cbranch_execnz .Lsel_cand1_loop
.Lsel_cand1_done:
	s_mov_b64 exec, s[0:1]
.Lsel_cand_done:
	v_bcnt_u32_b32 v0, v196, 0
	v_bcnt_u32_b32 v0, v197, v0
	v_mov_b32_e32 v1, v0
	s_nop 1
	v_add_u32_dpp v1, v1, v1 row_shr:1 row_mask:0xf bank_mask:0xf
	s_nop 1
	v_add_u32_dpp v1, v1, v1 row_shr:2 row_mask:0xf bank_mask:0xf
	s_nop 1
	v_add_u32_dpp v1, v1, v1 row_shr:4 row_mask:0xf bank_mask:0xf
	s_nop 1
	v_add_u32_dpp v1, v1, v1 row_shr:8 row_mask:0xf bank_mask:0xf
	s_nop 1
	v_add_u32_dpp v1, v1, v1 row_bcast:15 row_mask:0xa bank_mask:0xf
	s_nop 1
	v_add_u32_dpp v1, v1, v1 row_bcast:31 row_mask:0xc bank_mask:0xf
	s_nop 1
	v_readlane_b32 s4, v1, 63
	v_sub_u32_e32 v200, v1, v0
	s_sub_i32 s2, s61, s4
	s_cmp_eq_u32 s38, 0
	s_cselect_b32 s2, 0, s2
	v_add_u32_e32 v200, s2, v200
	v_cmp_ne_u32_e32 vcc, 0, v196
	s_and_saveexec_b64 s[0:1], vcc
	s_cbranch_execz .Lsel_abv0_done
.Lsel_abv0_loop:
	v_ffbh_u32_e32 v1, v196
	v_lshrrev_b32_e32 v2, v1, v204
	v_xor_b32_e32 v196, v196, v2
	v_lshl_add_u32 v3, v1, 7, v180
	s_mov_b64 s[6:7], exec
	v_cmp_gt_u32_e32 vcc, 0x100, v200
	v_lshlrev_b32_e32 v4, 1, v200
	s_and_b64 exec, exec, vcc
	global_store_short v4, v3, s[62:63]
	s_mov_b64 exec, s[6:7]
	v_add_u32_e32 v200, 1, v200
	v_cmp_ne_u32_e32 vcc, 0, v196
	s_and_b64 exec, exec, vcc
	s_cbranch_execnz .Lsel_abv0_loop
.Lsel_abv0_done:
	s_mov_b64 exec, s[0:1]
	v_cmp_ne_u32_e32 vcc, 0, v197
	s_and_saveexec_b64 s[0:1], vcc
	s_cbranch_execz .Lsel_abv1_done
.Lsel_abv1_loop:
	v_ffbh_u32_e32 v1, v197
	v_lshrrev_b32_e32 v2, v1, v204
	v_xor_b32_e32 v197, v197, v2
	v_lshl_add_u32 v3, v1, 7, v180
	v_add_u32_e32 v3, 0x1000, v3
	s_mov_b64 s[6:7], exec
	v_cmp_gt_u32_e32 vcc, 0x100, v200
	v_lshlrev_b32_e32 v4, 1, v200
	s_and_b64 exec, exec, vcc
	global_store_short v4, v3, s[62:63]
	s_mov_b64 exec, s[6:7]
	v_add_u32_e32 v200, 1, v200
	v_cmp_ne_u32_e32 vcc, 0, v197
	s_and_b64 exec, exec, vcc
	s_cbranch_execnz .Lsel_abv1_loop
.Lsel_abv1_done:
	s_mov_b64 exec, s[0:1]
	s_branch .Lsel_D_skip
.Lsel_fallback:
	s_mov_b32 s65, 1
	ds_write_b32 v207, v206 offset:24
.Lsel_D_skip:
	s_waitcnt lgkmcnt(0)
	s_barrier
	s_cmp_lg_u32 s65, 0
	s_cbranch_scc1 .Lsel_rank_skip
	v_cmp_gt_u32_e32 vcc, s60, v180
	s_and_saveexec_b64 s[0:1], vcc
	s_cbranch_execz .Lsel_rank_done
	v_lshl_add_u32 v0, v180, 3, s43
	ds_read_b64 v[202:203], v0
	v_mov_b32_e32 v201, 0
	s_mov_b32 s2, s43
	s_add_i32 s3, s60, 3
	s_lshr_b32 s3, s3, 2
.Lsel_rank_loop:
	v_mov_b32_e32 v1, s2
	ds_read_b128 v[4:7], v1
	ds_read_b128 v[8:11], v1 offset:16
	s_waitcnt lgkmcnt(0)
	v_cmp_gt_u64_e64 s[46:47], v[4:5], v[202:203]
	v_cmp_gt_u64_e64 s[48:49], v[6:7], v[202:203]
	v_cmp_gt_u64_e64 s[50:51], v[8:9], v[202:203]
	v_cmp_gt_u64_e64 s[54:55], v[10:11], v[202:203]
	v_addc_co_u32_e64 v201, s[56:57], 0, v201, s[46:47]
	v_addc_co_u32_e64 v201, s[56:57], 0, v201, s[48:49]
	v_addc_co_u32_e64 v201, s[56:57], 0, v201, s[50:51]
	v_addc_co_u32_e64 v201, s[56:57], 0, v201, s[54:55]
	s_add_i32 s2, s2, 32
	s_add_i32 s3, s3, -1
	s_cmp_lg_u32 s3, 0
	s_cbranch_scc1 .Lsel_rank_loop
	v_cmp_gt_u32_e32 vcc, s59, v201
	v_bfe_u32 v2, v202, 3, 13
	v_add_u32_e32 v3, s61, v201
	s_and_b64 exec, exec, vcc
	v_sub_u32_e32 v2, 0x1fff, v2
	v_cmp_gt_u32_e32 vcc, 0x100, v3
	v_lshlrev_b32_e32 v3, 1, v3
	s_and_b64 exec, exec, vcc
	global_store_short v3, v2, s[62:63]

; DI void lds_barrier() { asm volatile("s_waitcnt lgkmcnt(0)" ::: "memory"); __builtin_amdgcn_s_barrier(); asm volatile("" ::: "memory"); }
; DI float ord2f(unsigned k) { return __uint_as_float((k & 0x80000000u) ? (k ^ 0x80000000u) : ~k); }
; DI int block_excl_scan(int v, int* tmp, int* tot) {
;     ...
;   for (int o = 1; o < 64; o <<= 1) { const int u = __shfl_up(inc, o); if (lane >= o) inc += u; }
; DI void selectA_item(const Params& p, int item, int next_item, char* lds, bf16x8 (&qf)[4], float (&wq)[16]) {
;     ...
;     lds_barrier();
;   }
;   for (int q = 0; q < 4; ++q) {
;     if (misc[32 + q * 8 + 6]) { const int t = t0 + q; select_slow(sc + q * 8192, t + 1, SEL + (rowb + t) * 256, ord2f(mm[q * 2]), ord2f(mm[q * 2 + 1]), hist, misc, clist); }
;   }
;   lds_barrier();
.Lsel_rank_skip:
	v_subrev_u32_e32 v0, 1, v183
	v_cmp_gt_i32_e32 vcc, 0, v0
	s_nop 1
	v_cndmask_b32_e32 v0, v0, v183, vcc
	v_lshlrev_b32_e32 v69, 2, v0
	v_subrev_u32_e32 v0, 2, v183
	v_cmp_gt_i32_e32 vcc, 0, v0
	s_nop 1
	v_cndmask_b32_e32 v0, v0, v183, vcc
	v_lshlrev_b32_e32 v73, 2, v0
	v_subrev_u32_e32 v0, 4, v183
	v_cmp_gt_i32_e32 vcc, 0, v0
	s_nop 1
	v_cndmask_b32_e32 v0, v0, v183, vcc
	v_lshlrev_b32_e32 v77, 2, v0
	v_subrev_u32_e32 v0, 8, v183
	v_cmp_gt_i32_e32 vcc, 0, v0
	s_nop 1
	v_cndmask_b32_e32 v0, v0, v183, vcc
	v_lshlrev_b32_e32 v81, 2, v0
	v_subrev_u32_e32 v0, 16, v183
	v_cmp_gt_i32_e32 vcc, 0, v0
	s_nop 1
	v_cndmask_b32_e32 v0, v0, v183, vcc
	v_lshlrev_b32_e32 v189, 2, v0
	v_subrev_u32_e32 v0, 32, v183
	v_cmp_gt_i32_e32 vcc, 0, v0
	s_nop 1
	v_cndmask_b32_e32 v0, v0, v183, vcc
	v_lshlrev_b32_e32 v190, 2, v0
	s_waitcnt lgkmcnt(0)
	s_barrier
	s_mov_b32 s15, 0
	s_branch .LBB0_1322

; DI void lds_fence() { asm volatile("s_waitcnt lgkmcnt(0)" ::: "memory"); __builtin_amdgcn_wave_barrier(); }
; #define A_LOAD(j) do { _Pragma("unroll") for (int i = 0; i < 4; ++i) { const int row = (lane >> 3) + 8 * i, ch = lane & 7, e = 32 * (j) + row; \
;       const int tokk = (e < count) ? (int)sel_l[e] : 0; const size_t off = (size_t)tokk * NPE + ch * 8; R.k[i] = *(const u32x4*)(Kg + off); R.v[i] = *(const u32x4*)(Vg + off); } } while (0)
; DI void mixerA_item(const Params& p, int item, bf16* Ks, bf16* Vs, int lane) {
;   const bf16* PE = (const bf16*)(p.ws + WS_PE); bf16* Y = (bf16*)(p.ws + WS_Y);
;   const unsigned short* SEL = (const unsigned short*)(p.ws + WS_SEL) + (size_t)item * 256;
;   const int t = item & (SEQ - 1), b = item >> 13;
;   const int c = lane & 15, qd = lane >> 4, head = c & 7;
;   const size_t rowb = (size_t)b * SEQ;
;   const int count = (t + 1 < 256) ? t + 1 : 256, nsteps = (count + 31) >> 5;
;   bf16x8 qf[2];
; #pragma unroll
;   for (int ks = 0; ks < 2; ++ks) qf[ks] = *(const bf16x8*)(PE + (size_t)item * NPE + E_AQ + head * 64 + ks * 32 + qd * 8);
;   f32x4 o[4];
; #pragma unroll
;   for (int d = 0; d < 4; ++d) o[d] = (f32x4){0.f, 0.f, 0.f, 0.f};
;   float m = -1e30f, l = 0.f;
;   const bf16* Kg = PE + rowb * NPE + E_AK; const bf16* Vg = PE + rowb * NPE + E_AV;
;   KVRegs R;
;   unsigned short* sel_l = (unsigned short*)(Vs + 32 * WP);
;   lds_fence();
;   *(u32x2*)(sel_l + 4 * lane) = *(const u32x2*)(SEL + 4 * lane);
;   lds_fence();
;     ...
;   A_LOAD(0);
; __global__ void __launch_bounds__(NTHREADS) fwd_kernel(Params p) {
;     ...
;   { FRESH_IDS
;     ...
;     const int nK = (2 * 2048 + (int)gridDim.x - 1) / (int)gridDim.x;
;     for (int rep = 0; rep < REP_AATT; ++rep)
;       for (int s2 = wid; s2 < nK * 4; s2 += 8) { const int it = SEL_ITEM(s2 >> 2); if (it < 2 * 2048) mixerA_item(p, (it >> 11) * SEQ + (it & 2047) * 4 + (s2 & 3), Ks, Vs, lane); }
.LBB0_1893:
	s_or_b64 exec, exec, s[2:3]
	v_and_b32_e32 v1, 0x8000, v18
	v_cmp_ne_u32_e32 vcc, 0, v1
	v_cmp_gt_i32_e64 s[36:37], s12, v0
	s_and_b64 s[4:5], vcc, s[36:37]
	s_and_saveexec_b64 s[2:3], s[4:5]
	s_cbranch_execz .LBB0_1320
	v_ashrrev_i32_e32 v1, 31, v0
	v_lshl_add_u64 v[0:1], v[0:1], 1, s[0:1]
	global_store_short v[0:1], v205, off
	s_branch .LBB0_1320
.LBB0_2143:
	v_readlane_b32 s2, v254, 3
	v_readlane_b32 s3, v254, 4
	s_barrier
	s_load_dwordx2 s[0:1], s[2:3], 0x158
	v_mov_b32_e32 v0, v182
	s_waitcnt lgkmcnt(0)
	s_mov_b64 s[2:3], s[0:1]
	s_abs_i32 s0, s2
	v_cvt_f32_u32_e32 v1, s0
	s_sub_i32 s3, 0, s0
	s_add_i32 s1, s2, 0xfff
	s_xor_b32 s2, s1, s2
	v_rcp_iflag_f32_e32 v1, v1
	s_abs_i32 s1, s1
	s_ashr_i32 s2, s2, 31
	v_ashrrev_i32_e32 v73, 6, v0
	v_mul_f32_e32 v1, 0x4f7ffffe, v1
	v_cvt_u32_f32_e32 v1, v1
	s_nop 0
	v_readfirstlane_b32 s4, v1
	s_mul_i32 s3, s3, s4
	s_mul_hi_u32 s3, s4, s3
	s_add_i32 s4, s4, s3
	s_mul_hi_u32 s3, s1, s4
	s_mul_i32 s4, s3, s0
	s_sub_i32 s1, s1, s4
	s_add_i32 s4, s3, 1
	s_sub_i32 s5, s1, s0
	s_cmp_ge_u32 s1, s0
	s_cselect_b32 s3, s4, s3
	s_cselect_b32 s1, s5, s1
	s_add_i32 s4, s3, 1
	s_cmp_ge_u32 s1, s0
	s_cselect_b32 s0, s4, s3
	s_xor_b32 s0, s0, s2
	s_sub_i32 s0, s0, s2
	s_lshl_b32 s24, s0, 2
	v_cmp_gt_i32_e32 vcc, s24, v73
	s_and_saveexec_b64 s[0:1], vcc
	v_readlane_b32 s33, v254, 12
	s_cbranch_execz .LBB0_2171
	s_movk_i32 s2, 0x2600
	v_mul_lo_u32 v6, v73, s2
	v_readlane_b32 s2, v254, 3
	v_readlane_b32 s3, v254, 4
	s_load_dwordx2 s[2:3], s[2:3], 0xd0
	v_and_b32_e32 v1, 63, v0
	v_mov_b32_e32 v69, 0
	v_lshlrev_b32_e32 v2, 3, v1
	v_mov_b32_e32 v3, v69
	v_bfe_u32 v88, v0, 3, 3
	v_lshlrev_b32_e32 v1, 3, v0
	s_waitcnt lgkmcnt(0)
	v_lshl_add_u64 v[4:5], s[2:3], 0, v[2:3]
	v_and_b32_e32 v72, 56, v1
	v_mul_u32_u24_e32 v3, 0x48, v88
	v_add_u32_e32 v7, 0, v6
	v_lshlrev_b32_e32 v1, 1, v72
	v_lshlrev_b32_e32 v3, 1, v3
	v_add3_u32 v93, v7, v1, v3
	v_and_b32_e32 v1, 15, v0
	v_bfe_u32 v8, v0, 4, 2
	v_mul_u32_u24_e32 v1, 0x90, v1
	v_and_b32_e32 v3, 48, v0
	v_add3_u32 v94, v7, v1, v3
	v_lshlrev_b32_e32 v74, 2, v8
	v_bfe_u32 v1, v0, 2, 2
	v_or_b32_e32 v1, v74, v1
	v_add_u32_e32 v75, v7, v2
	v_mul_u32_u24_e32 v1, 0x90, v1
	v_and_b32_e32 v2, 24, v2
	v_add3_u32 v102, v7, v1, v2
	v_lshlrev_b32_e32 v1, 7, v0
	v_and_b32_e32 v2, 0x380, v1
	v_mov_b32_e32 v3, v69
	v_lshlrev_b32_e32 v68, 3, v8
	s_mov_b64 s[4:5], 0xda00000
	v_lshl_add_u64 v[76:77], s[2:3], 0, v[2:3]
	v_and_b32_e32 v9, 8, v0
	v_lshl_add_u64 v[70:71], v[4:5], 0, s[4:5]
	v_lshlrev_b32_e32 v4, 1, v88
	v_bfe_u32 v103, v0, 6, 2
	v_lshl_add_u64 v[0:1], v[76:77], 0, v[68:69]
	s_mov_b64 s[6:7], 0xa000000
	v_lshl_add_u64 v[78:79], v[0:1], 0, s[6:7]
	v_or_b32_e32 v0, v6, v4
	v_add_u32_e32 v0, 0, v0
	v_add_u32_e32 v89, v7, v4
	v_or_b32_e32 v90, 8, v88
	v_or_b32_e32 v91, 16, v88
	v_or_b32_e32 v92, 24, v88
	v_or_b32_e32 v95, 16, v74
	v_or_b32_e32 v96, 1, v74
	v_or_b32_e32 v97, 17, v74
	v_or_b32_e32 v98, 2, v74
	v_or_b32_e32 v99, 18, v74
	v_or_b32_e32 v100, 3, v74
	v_or_b32_e32 v101, 19, v74
	v_cmp_eq_u32_e64 s[4:5], 0, v9
	v_add_u32_e32 v104, 0x2440, v0
	v_or_b32_e32 v105, 56, v88
	s_mov_b64 s[18:19], 0
	v_mov_b32_e32 v106, s15
	v_mov_b32_e32 v107, s33
	s_movk_i32 s25, 0x1000
	s_movk_i32 s26, 0x1fff
	s_movk_i32 s27, 0x1800
	v_lshlrev_b32_e32 v80, 1, v68
	s_mov_b32 s28, 0x3000000
	s_mov_b32 s29, 0xff800000
	s_mov_b32 s30, 0x3e38aa3b
	v_mov_b32_e32 v108, 0xff800000
	s_branch .LBB0_2146
